# counted waits in the context-row GEMM K-loops: fragment loads issued four K-steps ahead into rotating register sets (vmcnt counted instead of 0 after every step)
# speedup vs baseline: 1.0140x; 1.0009x over previous
; #define MFMA32(a, b, c) __builtin_amdgcn_mfma_f32_32x32x16_bf16((a), (b), (c), 0, 0, 0)
; template <class Fin> __device__ __forceinline__ void ctx_gemm(const bf16_t* A, int lda, const bf16_t* Bt, int K, const Fin& fin, uchar* lds) {
;     ...
;     for (int id = blockIdx.x; id < 256; id += gridDim.x) {
;         const int tr = id >> 3, tc = id & 7;
;         const bf16_t* ap = A + (size_t)(tr * 32 + l32) * lda + wave * kw + 8 * hi;
;         const bf16_t* bp = Bt + (size_t)(tc * 128 + l32) * K + wave * kw + 8 * hi;
;         f32x16 acc0 = {}, acc1 = {}, acc2 = {}, acc3 = {};
; #pragma unroll 8
;         for (int s = 0; s < nst; ++s) {
;             const bf16x8 af = *(const bf16x8*)(ap + 16 * s);
;             const bf16x8 b0 = *(const bf16x8*)(bp + 16 * s), b1 = *(const bf16x8*)(bp + (size_t)32 * K + 16 * s), b2 = *(const bf16x8*)(bp + (size_t)64 * K + 16 * s), b3 = *(const bf16x8*)(bp + (size_t)96 * K + 16 * s);
;             acc0 = MFMA32(af, b0, acc0); acc1 = MFMA32(af, b1, acc1); acc2 = MFMA32(af, b2, acc2); acc3 = MFMA32(af, b3, acc3);
;         }
.LBB0_489:
	s_and_b32 s7, s4, 0xffffffe0
	v_or_b32_e32 v0, s7, v80
	v_mad_i64_i32 v[78:79], s[8:9], v0, s16, v[66:67]
	s_and_b32 s8, s5, 0x380
	s_nop 0
	v_or_b32_e32 v0, s8, v80
	v_mul_u32_u24_e32 v0, 0xb00, v0
	v_lshlrev_b32_e32 v0, 1, v0
	v_lshl_add_u64 v[74:75], v[68:69], 0, v[0:1]
	v_add_co_u32_e32 v76, vcc, 0x2c000, v74
	global_load_dwordx4 v[50:53], v[78:79], off
	global_load_dwordx4 v[2:5], v[74:75], off
	v_addc_co_u32_e32 v77, vcc, 0, v75, vcc
	v_add_co_u32_e32 v72, vcc, 0x58000, v74
	s_waitcnt lgkmcnt(0)
	global_load_dwordx4 v[18:21], v[76:77], off
	v_addc_co_u32_e32 v73, vcc, 0, v75, vcc
	v_add_co_u32_e32 v70, vcc, 0x84000, v74
	global_load_dwordx4 v[34:37], v[72:73], off
	s_nop 0
	v_addc_co_u32_e32 v71, vcc, 0, v75, vcc
	global_load_dwordx4 v[54:57], v[70:71], off
	global_load_dwordx4 v[94:97], v[78:79], off offset:32
	global_load_dwordx4 v[98:101], v[74:75], off offset:32
	global_load_dwordx4 v[102:105], v[76:77], off offset:32
	global_load_dwordx4 v[106:109], v[72:73], off offset:32
	global_load_dwordx4 v[110:113], v[70:71], off offset:32
	v_add_u32_e32 v0, 0x400, v81
	s_add_i32 s6, s6, s90
	s_add_i32 s5, s5, s17
	s_add_i32 s4, s4, s64
	s_cmpk_lt_i32 s6, 0x100
	global_load_dwordx4 v[146:149], v[78:79], off offset:64
	global_load_dwordx4 v[150:153], v[74:75], off offset:64
	global_load_dwordx4 v[154:157], v[76:77], off offset:64
	global_load_dwordx4 v[158:161], v[72:73], off offset:64
	global_load_dwordx4 v[162:165], v[70:71], off offset:64
	global_load_dwordx4 v[166:169], v[78:79], off offset:96
	global_load_dwordx4 v[170:173], v[74:75], off offset:96
	global_load_dwordx4 v[174:177], v[76:77], off offset:96
	global_load_dwordx4 v[178:181], v[72:73], off offset:96
	global_load_dwordx4 v[182:185], v[70:71], off offset:96
	global_load_dwordx4 v[194:197], v[78:79], off offset:128
	global_load_dwordx4 v[198:201], v[74:75], off offset:128
	global_load_dwordx4 v[202:205], v[76:77], off offset:128
	global_load_dwordx4 v[220:223], v[72:73], off offset:128
	global_load_dwordx4 v[224:227], v[70:71], off offset:128
	s_waitcnt vmcnt(15)
	v_mfma_f32_32x32x16_bf16 v[2:17], v[50:53], v[2:5], 0
	v_mfma_f32_32x32x16_bf16 v[18:33], v[50:53], v[18:21], 0
	v_mfma_f32_32x32x16_bf16 v[34:49], v[50:53], v[34:37], 0
	v_mfma_f32_32x32x16_bf16 v[50:65], v[50:53], v[54:57], 0
	v_mfma_f32_32x32x16_bf16 v[2:17], v[94:97], v[98:101], v[2:17]
	v_mfma_f32_32x32x16_bf16 v[18:33], v[94:97], v[102:105], v[18:33]
	v_mfma_f32_32x32x16_bf16 v[34:49], v[94:97], v[106:109], v[34:49]
	v_mfma_f32_32x32x16_bf16 v[50:65], v[94:97], v[110:113], v[50:65]
	global_load_dwordx4 v[94:97], v[78:79], off offset:160
	global_load_dwordx4 v[98:101], v[74:75], off offset:160
	global_load_dwordx4 v[102:105], v[76:77], off offset:160
	global_load_dwordx4 v[106:109], v[72:73], off offset:160
	global_load_dwordx4 v[110:113], v[70:71], off offset:160
	s_waitcnt vmcnt(18)
	v_mfma_f32_32x32x16_bf16 v[2:17], v[146:149], v[150:153], v[2:17]
	s_waitcnt vmcnt(17)
	v_mfma_f32_32x32x16_bf16 v[18:33], v[146:149], v[154:157], v[18:33]
	s_waitcnt vmcnt(16)
	v_mfma_f32_32x32x16_bf16 v[34:49], v[146:149], v[158:161], v[34:49]
	s_waitcnt vmcnt(15)
	v_mfma_f32_32x32x16_bf16 v[50:65], v[146:149], v[162:165], v[50:65]
	global_load_dwordx4 v[146:149], v[78:79], off offset:192
	global_load_dwordx4 v[150:153], v[74:75], off offset:192
	global_load_dwordx4 v[154:157], v[76:77], off offset:192
	global_load_dwordx4 v[158:161], v[72:73], off offset:192
	global_load_dwordx4 v[162:165], v[70:71], off offset:192
	s_waitcnt vmcnt(18)
	v_mfma_f32_32x32x16_bf16 v[2:17], v[166:169], v[170:173], v[2:17]
	s_waitcnt vmcnt(17)
	v_mfma_f32_32x32x16_bf16 v[18:33], v[166:169], v[174:177], v[18:33]
	s_waitcnt vmcnt(16)
	v_mfma_f32_32x32x16_bf16 v[34:49], v[166:169], v[178:181], v[34:49]
	s_waitcnt vmcnt(15)
	v_mfma_f32_32x32x16_bf16 v[50:65], v[166:169], v[182:185], v[50:65]
	global_load_dwordx4 v[166:169], v[78:79], off offset:224
	global_load_dwordx4 v[170:173], v[74:75], off offset:224
	global_load_dwordx4 v[174:177], v[76:77], off offset:224
	global_load_dwordx4 v[178:181], v[72:73], off offset:224
	global_load_dwordx4 v[182:185], v[70:71], off offset:224
	s_waitcnt vmcnt(18)
	v_mfma_f32_32x32x16_bf16 v[2:17], v[194:197], v[198:201], v[2:17]
	s_waitcnt vmcnt(17)
	v_mfma_f32_32x32x16_bf16 v[18:33], v[194:197], v[202:205], v[18:33]
	s_waitcnt vmcnt(16)
	v_mfma_f32_32x32x16_bf16 v[34:49], v[194:197], v[220:223], v[34:49]
	s_waitcnt vmcnt(15)
	v_mfma_f32_32x32x16_bf16 v[50:65], v[194:197], v[224:227], v[50:65]
	global_load_dwordx4 v[194:197], v[78:79], off offset:256
	global_load_dwordx4 v[198:201], v[74:75], off offset:256
	global_load_dwordx4 v[202:205], v[76:77], off offset:256
	global_load_dwordx4 v[220:223], v[72:73], off offset:256
	global_load_dwordx4 v[224:227], v[70:71], off offset:256
	s_waitcnt vmcnt(18)
	v_mfma_f32_32x32x16_bf16 v[2:17], v[94:97], v[98:101], v[2:17]
	s_waitcnt vmcnt(17)
	v_mfma_f32_32x32x16_bf16 v[18:33], v[94:97], v[102:105], v[18:33]
	s_waitcnt vmcnt(16)
	v_mfma_f32_32x32x16_bf16 v[34:49], v[94:97], v[106:109], v[34:49]
	s_waitcnt vmcnt(15)
	v_mfma_f32_32x32x16_bf16 v[50:65], v[94:97], v[110:113], v[50:65]
	global_load_dwordx4 v[94:97], v[78:79], off offset:288
	global_load_dwordx4 v[98:101], v[74:75], off offset:288
	global_load_dwordx4 v[102:105], v[76:77], off offset:288
	global_load_dwordx4 v[106:109], v[72:73], off offset:288
	global_load_dwordx4 v[110:113], v[70:71], off offset:288
	s_waitcnt vmcnt(18)
	v_mfma_f32_32x32x16_bf16 v[2:17], v[146:149], v[150:153], v[2:17]
	s_waitcnt vmcnt(17)
	v_mfma_f32_32x32x16_bf16 v[18:33], v[146:149], v[154:157], v[18:33]
	s_waitcnt vmcnt(16)
; #define MFMA32(a, b, c) __builtin_amdgcn_mfma_f32_32x32x16_bf16((a), (b), (c), 0, 0, 0)
; template <class Fin> __device__ __forceinline__ void ctx_gemm(const bf16_t* A, int lda, const bf16_t* Bt, int K, const Fin& fin, uchar* lds) {
;     ...
; #pragma unroll 8
;         for (int s = 0; s < nst; ++s) {
;             const bf16x8 af = *(const bf16x8*)(ap + 16 * s);
;             const bf16x8 b0 = *(const bf16x8*)(bp + 16 * s), b1 = *(const bf16x8*)(bp + (size_t)32 * K + 16 * s), b2 = *(const bf16x8*)(bp + (size_t)64 * K + 16 * s), b3 = *(const bf16x8*)(bp + (size_t)96 * K + 16 * s);
;             acc0 = MFMA32(af, b0, acc0); acc1 = MFMA32(af, b1, acc1); acc2 = MFMA32(af, b2, acc2); acc3 = MFMA32(af, b3, acc3);
;         }
	v_mfma_f32_32x32x16_bf16 v[34:49], v[146:149], v[158:161], v[34:49]
	s_waitcnt vmcnt(15)
	v_mfma_f32_32x32x16_bf16 v[50:65], v[146:149], v[162:165], v[50:65]
	global_load_dwordx4 v[146:149], v[78:79], off offset:320
	global_load_dwordx4 v[150:153], v[74:75], off offset:320
	global_load_dwordx4 v[154:157], v[76:77], off offset:320
	global_load_dwordx4 v[158:161], v[72:73], off offset:320
	global_load_dwordx4 v[162:165], v[70:71], off offset:320
	s_waitcnt vmcnt(18)
	v_mfma_f32_32x32x16_bf16 v[2:17], v[166:169], v[170:173], v[2:17]
	s_waitcnt vmcnt(17)
	v_mfma_f32_32x32x16_bf16 v[18:33], v[166:169], v[174:177], v[18:33]
	s_waitcnt vmcnt(16)
	v_mfma_f32_32x32x16_bf16 v[34:49], v[166:169], v[178:181], v[34:49]
	s_waitcnt vmcnt(15)
	v_mfma_f32_32x32x16_bf16 v[50:65], v[166:169], v[182:185], v[50:65]
	global_load_dwordx4 v[166:169], v[78:79], off offset:352
	global_load_dwordx4 v[170:173], v[74:75], off offset:352
	global_load_dwordx4 v[174:177], v[76:77], off offset:352
	global_load_dwordx4 v[178:181], v[72:73], off offset:352
	global_load_dwordx4 v[182:185], v[70:71], off offset:352
	s_waitcnt vmcnt(18)
	v_mfma_f32_32x32x16_bf16 v[2:17], v[194:197], v[198:201], v[2:17]
	s_waitcnt vmcnt(17)
	v_mfma_f32_32x32x16_bf16 v[18:33], v[194:197], v[202:205], v[18:33]
	s_waitcnt vmcnt(16)
	v_mfma_f32_32x32x16_bf16 v[34:49], v[194:197], v[220:223], v[34:49]
	s_waitcnt vmcnt(15)
	v_mfma_f32_32x32x16_bf16 v[50:65], v[194:197], v[224:227], v[50:65]
	global_load_dwordx4 v[194:197], v[78:79], off offset:384
	global_load_dwordx4 v[198:201], v[74:75], off offset:384
	global_load_dwordx4 v[202:205], v[76:77], off offset:384
	global_load_dwordx4 v[220:223], v[72:73], off offset:384
	global_load_dwordx4 v[224:227], v[70:71], off offset:384
	s_waitcnt vmcnt(18)
	v_mfma_f32_32x32x16_bf16 v[2:17], v[94:97], v[98:101], v[2:17]
	s_waitcnt vmcnt(17)
	v_mfma_f32_32x32x16_bf16 v[18:33], v[94:97], v[102:105], v[18:33]
	s_waitcnt vmcnt(16)
	v_mfma_f32_32x32x16_bf16 v[34:49], v[94:97], v[106:109], v[34:49]
	s_waitcnt vmcnt(15)
	v_mfma_f32_32x32x16_bf16 v[50:65], v[94:97], v[110:113], v[50:65]
	global_load_dwordx4 v[94:97], v[78:79], off offset:416
	global_load_dwordx4 v[98:101], v[74:75], off offset:416
	global_load_dwordx4 v[102:105], v[76:77], off offset:416
	global_load_dwordx4 v[106:109], v[72:73], off offset:416
	global_load_dwordx4 v[110:113], v[70:71], off offset:416
	s_waitcnt vmcnt(18)
	v_mfma_f32_32x32x16_bf16 v[2:17], v[146:149], v[150:153], v[2:17]
	s_waitcnt vmcnt(17)
	v_mfma_f32_32x32x16_bf16 v[18:33], v[146:149], v[154:157], v[18:33]
	s_waitcnt vmcnt(16)
	v_mfma_f32_32x32x16_bf16 v[34:49], v[146:149], v[158:161], v[34:49]
	s_waitcnt vmcnt(15)
	v_mfma_f32_32x32x16_bf16 v[50:65], v[146:149], v[162:165], v[50:65]
	global_load_dwordx4 v[146:149], v[78:79], off offset:448
	global_load_dwordx4 v[150:153], v[74:75], off offset:448
	global_load_dwordx4 v[154:157], v[76:77], off offset:448
	global_load_dwordx4 v[158:161], v[72:73], off offset:448
	global_load_dwordx4 v[162:165], v[70:71], off offset:448
	s_waitcnt vmcnt(18)
	v_mfma_f32_32x32x16_bf16 v[2:17], v[166:169], v[170:173], v[2:17]
	s_waitcnt vmcnt(17)
	v_mfma_f32_32x32x16_bf16 v[18:33], v[166:169], v[174:177], v[18:33]
	s_waitcnt vmcnt(16)
	v_mfma_f32_32x32x16_bf16 v[34:49], v[166:169], v[178:181], v[34:49]
	s_waitcnt vmcnt(15)
	v_mfma_f32_32x32x16_bf16 v[50:65], v[166:169], v[182:185], v[50:65]
	global_load_dwordx4 v[166:169], v[78:79], off offset:480
	global_load_dwordx4 v[170:173], v[74:75], off offset:480
	global_load_dwordx4 v[174:177], v[76:77], off offset:480
	global_load_dwordx4 v[178:181], v[72:73], off offset:480
	global_load_dwordx4 v[182:185], v[70:71], off offset:480
	s_waitcnt vmcnt(18)
	v_mfma_f32_32x32x16_bf16 v[2:17], v[194:197], v[198:201], v[2:17]
	s_waitcnt vmcnt(17)
	v_mfma_f32_32x32x16_bf16 v[18:33], v[194:197], v[202:205], v[18:33]
	s_waitcnt vmcnt(16)
	v_mfma_f32_32x32x16_bf16 v[34:49], v[194:197], v[220:223], v[34:49]
	s_waitcnt vmcnt(15)
	v_mfma_f32_32x32x16_bf16 v[50:65], v[194:197], v[224:227], v[50:65]
	global_load_dwordx4 v[194:197], v[78:79], off offset:512
	global_load_dwordx4 v[198:201], v[74:75], off offset:512
	global_load_dwordx4 v[202:205], v[76:77], off offset:512
	global_load_dwordx4 v[220:223], v[72:73], off offset:512
	global_load_dwordx4 v[224:227], v[70:71], off offset:512
	s_waitcnt vmcnt(18)
	v_mfma_f32_32x32x16_bf16 v[2:17], v[94:97], v[98:101], v[2:17]
	s_waitcnt vmcnt(17)
	v_mfma_f32_32x32x16_bf16 v[18:33], v[94:97], v[102:105], v[18:33]
	s_waitcnt vmcnt(16)
	v_mfma_f32_32x32x16_bf16 v[34:49], v[94:97], v[106:109], v[34:49]
	s_waitcnt vmcnt(15)
	v_mfma_f32_32x32x16_bf16 v[50:65], v[94:97], v[110:113], v[50:65]
	global_load_dwordx4 v[94:97], v[78:79], off offset:544
	global_load_dwordx4 v[98:101], v[74:75], off offset:544
	global_load_dwordx4 v[102:105], v[76:77], off offset:544
	global_load_dwordx4 v[106:109], v[72:73], off offset:544
	global_load_dwordx4 v[110:113], v[70:71], off offset:544
	s_waitcnt vmcnt(18)
	v_mfma_f32_32x32x16_bf16 v[2:17], v[146:149], v[150:153], v[2:17]
	s_waitcnt vmcnt(17)
	v_mfma_f32_32x32x16_bf16 v[18:33], v[146:149], v[154:157], v[18:33]
	s_waitcnt vmcnt(16)
	v_mfma_f32_32x32x16_bf16 v[34:49], v[146:149], v[158:161], v[34:49]
	s_waitcnt vmcnt(15)
	v_mfma_f32_32x32x16_bf16 v[50:65], v[146:149], v[162:165], v[50:65]
	global_load_dwordx4 v[146:149], v[78:79], off offset:576
	global_load_dwordx4 v[150:153], v[74:75], off offset:576
	global_load_dwordx4 v[154:157], v[76:77], off offset:576
	global_load_dwordx4 v[158:161], v[72:73], off offset:576
	global_load_dwordx4 v[162:165], v[70:71], off offset:576
	s_waitcnt vmcnt(18)
; __device__ __forceinline__ int crow(int r, int hi) { return (r & 3) + 8 * (r >> 2) + 4 * hi; }
; #define MFMA32(a, b, c) __builtin_amdgcn_mfma_f32_32x32x16_bf16((a), (b), (c), 0, 0, 0)
; template <class Fin> __device__ __forceinline__ void ctx_gemm(const bf16_t* A, int lda, const bf16_t* Bt, int K, const Fin& fin, uchar* lds) {
;     ...
; #pragma unroll 8
;         for (int s = 0; s < nst; ++s) {
;             const bf16x8 af = *(const bf16x8*)(ap + 16 * s);
;             const bf16x8 b0 = *(const bf16x8*)(bp + 16 * s), b1 = *(const bf16x8*)(bp + (size_t)32 * K + 16 * s), b2 = *(const bf16x8*)(bp + (size_t)64 * K + 16 * s), b3 = *(const bf16x8*)(bp + (size_t)96 * K + 16 * s);
;             acc0 = MFMA32(af, b0, acc0); acc1 = MFMA32(af, b1, acc1); acc2 = MFMA32(af, b2, acc2); acc3 = MFMA32(af, b3, acc3);
;         }
;         float* rw = red + wave * 4096 + l32;
; #pragma unroll
;         for (int r = 0; r < 16; ++r) { float* q = rw + crow(r, hi) * 128; q[0] = acc0[r]; q[32] = acc1[r]; q[64] = acc2[r]; q[96] = acc3[r]; }
;         __syncthreads();
	v_mfma_f32_32x32x16_bf16 v[2:17], v[166:169], v[170:173], v[2:17]
	s_waitcnt vmcnt(17)
	v_mfma_f32_32x32x16_bf16 v[18:33], v[166:169], v[174:177], v[18:33]
	s_waitcnt vmcnt(16)
	v_mfma_f32_32x32x16_bf16 v[34:49], v[166:169], v[178:181], v[34:49]
	s_waitcnt vmcnt(15)
	v_mfma_f32_32x32x16_bf16 v[50:65], v[166:169], v[182:185], v[50:65]
	global_load_dwordx4 v[166:169], v[78:79], off offset:608
	global_load_dwordx4 v[170:173], v[74:75], off offset:608
	global_load_dwordx4 v[174:177], v[76:77], off offset:608
	global_load_dwordx4 v[178:181], v[72:73], off offset:608
	global_load_dwordx4 v[182:185], v[70:71], off offset:608
	s_waitcnt vmcnt(18)
	v_mfma_f32_32x32x16_bf16 v[2:17], v[194:197], v[198:201], v[2:17]
	s_waitcnt vmcnt(17)
	v_mfma_f32_32x32x16_bf16 v[18:33], v[194:197], v[202:205], v[18:33]
	s_waitcnt vmcnt(16)
	v_mfma_f32_32x32x16_bf16 v[34:49], v[194:197], v[220:223], v[34:49]
	s_waitcnt vmcnt(15)
	v_mfma_f32_32x32x16_bf16 v[50:65], v[194:197], v[224:227], v[50:65]
	global_load_dwordx4 v[194:197], v[78:79], off offset:640
	global_load_dwordx4 v[198:201], v[74:75], off offset:640
	global_load_dwordx4 v[202:205], v[76:77], off offset:640
	global_load_dwordx4 v[220:223], v[72:73], off offset:640
	global_load_dwordx4 v[224:227], v[70:71], off offset:640
	s_waitcnt vmcnt(18)
	v_mfma_f32_32x32x16_bf16 v[2:17], v[94:97], v[98:101], v[2:17]
	s_waitcnt vmcnt(17)
	v_mfma_f32_32x32x16_bf16 v[18:33], v[94:97], v[102:105], v[18:33]
	s_waitcnt vmcnt(16)
	v_mfma_f32_32x32x16_bf16 v[34:49], v[94:97], v[106:109], v[34:49]
	s_waitcnt vmcnt(15)
	v_mfma_f32_32x32x16_bf16 v[50:65], v[94:97], v[110:113], v[50:65]
	global_load_dwordx4 v[94:97], v[78:79], off offset:672
	global_load_dwordx4 v[98:101], v[74:75], off offset:672
	global_load_dwordx4 v[102:105], v[76:77], off offset:672
	global_load_dwordx4 v[106:109], v[72:73], off offset:672
	global_load_dwordx4 v[110:113], v[70:71], off offset:672
	s_waitcnt vmcnt(18)
	v_mfma_f32_32x32x16_bf16 v[2:17], v[146:149], v[150:153], v[2:17]
	s_waitcnt vmcnt(17)
	v_mfma_f32_32x32x16_bf16 v[18:33], v[146:149], v[154:157], v[18:33]
	s_waitcnt vmcnt(16)
	v_mfma_f32_32x32x16_bf16 v[34:49], v[146:149], v[158:161], v[34:49]
	s_waitcnt vmcnt(15)
	v_mfma_f32_32x32x16_bf16 v[50:65], v[146:149], v[162:165], v[50:65]
	s_waitcnt vmcnt(13)
	v_mfma_f32_32x32x16_bf16 v[2:17], v[166:169], v[170:173], v[2:17]
	s_waitcnt vmcnt(12)
	v_mfma_f32_32x32x16_bf16 v[18:33], v[166:169], v[174:177], v[18:33]
	s_waitcnt vmcnt(11)
	v_mfma_f32_32x32x16_bf16 v[34:49], v[166:169], v[178:181], v[34:49]
	s_waitcnt vmcnt(10)
	v_mfma_f32_32x32x16_bf16 v[50:65], v[166:169], v[182:185], v[50:65]
	s_waitcnt vmcnt(8)
	v_mfma_f32_32x32x16_bf16 v[2:17], v[194:197], v[198:201], v[2:17]
	s_waitcnt vmcnt(7)
	v_mfma_f32_32x32x16_bf16 v[18:33], v[194:197], v[202:205], v[18:33]
	s_waitcnt vmcnt(6)
	v_mfma_f32_32x32x16_bf16 v[34:49], v[194:197], v[220:223], v[34:49]
	s_waitcnt vmcnt(5)
	v_mfma_f32_32x32x16_bf16 v[50:65], v[194:197], v[224:227], v[50:65]
	s_waitcnt vmcnt(3)
	v_mfma_f32_32x32x16_bf16 v[2:17], v[94:97], v[98:101], v[2:17]
	s_waitcnt vmcnt(2)
	v_mfma_f32_32x32x16_bf16 v[18:33], v[94:97], v[102:105], v[18:33]
	s_waitcnt vmcnt(1)
	v_mfma_f32_32x32x16_bf16 v[34:49], v[94:97], v[106:109], v[34:49]
	s_waitcnt vmcnt(0)
	v_mfma_f32_32x32x16_bf16 v[50:65], v[94:97], v[110:113], v[50:65]
	s_nop 7
	ds_write2_b32 v81, v2, v18 offset1:32
	s_nop 2
	ds_write2_b32 v81, v34, v50 offset0:64 offset1:96
	ds_write2_b32 v81, v3, v19 offset0:128 offset1:160
	ds_write2_b32 v81, v35, v51 offset0:192 offset1:224
	ds_write2_b32 v0, v4, v20 offset1:32
	ds_write2_b32 v0, v36, v52 offset0:64 offset1:96
	ds_write2_b32 v0, v5, v21 offset0:128 offset1:160
	ds_write2_b32 v0, v37, v53 offset0:192 offset1:224
	v_add_u32_e32 v0, 0x1000, v81
	ds_write2_b32 v0, v6, v22 offset1:32
	ds_write2_b32 v0, v38, v54 offset0:64 offset1:96
	ds_write2_b32 v0, v7, v23 offset0:128 offset1:160
	ds_write2_b32 v0, v39, v55 offset0:192 offset1:224
	v_add_u32_e32 v0, 0x1400, v81
	ds_write2_b32 v0, v8, v24 offset1:32
	ds_write2_b32 v0, v40, v56 offset0:64 offset1:96
	ds_write2_b32 v0, v9, v25 offset0:128 offset1:160
	ds_write2_b32 v0, v41, v57 offset0:192 offset1:224
	v_add_u32_e32 v0, 0x2000, v81
	ds_write2_b32 v0, v10, v26 offset1:32
	ds_write2_b32 v0, v42, v58 offset0:64 offset1:96
	ds_write2_b32 v0, v11, v27 offset0:128 offset1:160
	ds_write2_b32 v0, v43, v59 offset0:192 offset1:224
	v_add_u32_e32 v0, 0x2400, v81
	ds_write2_b32 v0, v12, v28 offset1:32
	ds_write2_b32 v0, v44, v60 offset0:64 offset1:96
	ds_write2_b32 v0, v13, v29 offset0:128 offset1:160
	ds_write2_b32 v0, v45, v61 offset0:192 offset1:224
	v_add_u32_e32 v0, 0x3000, v81
	ds_write2_b32 v0, v14, v30 offset1:32
	ds_write2_b32 v0, v46, v62 offset0:64 offset1:96
	ds_write2_b32 v0, v15, v31 offset0:128 offset1:160
	ds_write2_b32 v0, v47, v63 offset0:192 offset1:224
	v_add_u32_e32 v0, 0x3400, v81
	ds_write2_b32 v0, v16, v32 offset1:32
	ds_write2_b32 v0, v48, v64 offset0:64 offset1:96
	ds_write2_b32 v0, v17, v33 offset0:128 offset1:160
	ds_write2_b32 v0, v49, v65 offset0:192 offset1:224
	s_waitcnt lgkmcnt(0)
	s_barrier
; template <class Fin> __device__ __forceinline__ void ctx_gemm(const bf16_t* A, int lda, const bf16_t* Bt, int K, const Fin& fin, uchar* lds) {
;     ...
;         __syncthreads();
;         const int row = tid >> 4, c8 = (tid & 15) * 8;
;         f32x4 s0 = {}, s1 = {};
; #pragma unroll
;         for (int w = 0; w < 8; ++w) { s0 += *(const f32x4*)(red + w * 4096 + row * 128 + c8); s1 += *(const f32x4*)(red + w * 4096 + row * 128 + c8 + 4); }
;         fin(tr * 32 + row, tc * 128 + c8, s0, s1);
;         __syncthreads();
	ds_read_b128 v[2:5], v84
	ds_read_b128 v[6:9], v84 offset:16
	v_or_b32_e32 v0, s8, v83
	v_lshlrev_b32_e32 v0, 2, v0
	v_add_u32_e32 v18, s7, v82
	s_waitcnt lgkmcnt(1)
	v_pk_add_f32 v[10:11], v[4:5], 0 op_sel_hi:[1,0]
	v_pk_add_f32 v[12:13], v[2:3], 0 op_sel_hi:[1,0]
	ds_read_b128 v[2:5], v84 offset:16384
	s_waitcnt lgkmcnt(1)
	v_pk_add_f32 v[8:9], v[8:9], 0 op_sel_hi:[1,0]
	v_pk_add_f32 v[6:7], v[6:7], 0 op_sel_hi:[1,0]
	v_ashrrev_i32_e32 v19, 31, v18
	v_lshlrev_b64 v[18:19], 12, v[18:19]
	s_waitcnt lgkmcnt(0)
	v_pk_add_f32 v[10:11], v[10:11], v[4:5]
	v_pk_add_f32 v[12:13], v[12:13], v[2:3]
	ds_read_b128 v[2:5], v84 offset:16400
	v_or_b32_e32 v18, v18, v0
	s_waitcnt lgkmcnt(0)
	v_pk_add_f32 v[8:9], v[8:9], v[4:5]
	v_pk_add_f32 v[6:7], v[6:7], v[2:3]
	ds_read_b128 v[2:5], v84 offset:32768
	s_waitcnt lgkmcnt(0)
	v_pk_add_f32 v[10:11], v[10:11], v[4:5]
	v_pk_add_f32 v[12:13], v[12:13], v[2:3]
	ds_read_b128 v[2:5], v84 offset:32784
	s_waitcnt lgkmcnt(0)
	v_pk_add_f32 v[8:9], v[8:9], v[4:5]
	v_pk_add_f32 v[6:7], v[6:7], v[2:3]
	ds_read_b128 v[2:5], v84 offset:49152
	s_waitcnt lgkmcnt(0)
	v_pk_add_f32 v[10:11], v[10:11], v[4:5]
	v_pk_add_f32 v[12:13], v[12:13], v[2:3]
	ds_read_b128 v[2:5], v84 offset:49168
	s_waitcnt lgkmcnt(0)
	v_pk_add_f32 v[8:9], v[8:9], v[4:5]
	v_pk_add_f32 v[6:7], v[6:7], v[2:3]
	ds_read_b128 v[2:5], v85
	s_waitcnt lgkmcnt(0)
	v_pk_add_f32 v[10:11], v[10:11], v[4:5]
	v_pk_add_f32 v[12:13], v[12:13], v[2:3]
	ds_read_b128 v[2:5], v86
	s_waitcnt lgkmcnt(0)
	v_pk_add_f32 v[8:9], v[8:9], v[4:5]
	v_pk_add_f32 v[6:7], v[6:7], v[2:3]
	ds_read_b128 v[2:5], v87
	s_waitcnt lgkmcnt(0)
	v_pk_add_f32 v[10:11], v[10:11], v[4:5]
	v_pk_add_f32 v[12:13], v[12:13], v[2:3]
	ds_read_b128 v[2:5], v88
	s_waitcnt lgkmcnt(0)
	v_pk_add_f32 v[8:9], v[8:9], v[4:5]
	v_pk_add_f32 v[6:7], v[6:7], v[2:3]
	ds_read_b128 v[2:5], v89
	s_waitcnt lgkmcnt(0)
	v_pk_add_f32 v[10:11], v[10:11], v[4:5]
	v_pk_add_f32 v[12:13], v[12:13], v[2:3]
	ds_read_b128 v[2:5], v90
	s_waitcnt lgkmcnt(0)
	v_pk_add_f32 v[14:15], v[8:9], v[4:5]
	v_pk_add_f32 v[16:17], v[6:7], v[2:3]
	ds_read_b128 v[2:5], v91
	s_waitcnt lgkmcnt(0)
	v_pk_add_f32 v[6:7], v[10:11], v[4:5]
	v_pk_add_f32 v[8:9], v[12:13], v[2:3]
	ds_read_b128 v[10:13], v92
	s_waitcnt lgkmcnt(0)
	v_pk_add_f32 v[2:3], v[14:15], v[12:13]
	v_pk_add_f32 v[4:5], v[16:17], v[10:11]
	global_load_dwordx4 v[10:13], v0, s[36:37] offset:16
	global_load_dwordx4 v[14:17], v0, s[36:37]
	s_waitcnt vmcnt(1)
	v_pk_mul_f32 v[24:25], v[12:13], 0.5 op_sel_hi:[1,0]
	s_waitcnt vmcnt(0)
	v_pk_mul_f32 v[22:23], v[14:15], 0.5 op_sel_hi:[1,0]
	v_lshl_add_u64 v[14:15], s[56:57], 0, v[18:19]
	v_pk_mul_f32 v[20:21], v[16:17], 0.5 op_sel_hi:[1,0]
	v_pk_mul_f32 v[26:27], v[10:11], 0.5 op_sel_hi:[1,0]
	global_load_dwordx4 v[10:13], v[14:15], off offset:16
	s_nop 0
	global_load_dwordx4 v[14:17], v[14:15], off
	s_waitcnt vmcnt(1)
	v_pk_fma_f32 v[4:5], v[4:5], v[26:27], v[10:11]
	s_waitcnt vmcnt(0)
	v_pk_fma_f32 v[16:17], v[6:7], v[20:21], v[16:17]
	v_pk_fma_f32 v[14:15], v[8:9], v[22:23], v[14:15]
	v_lshl_add_u64 v[8:9], s[86:87], 0, v[18:19]
	v_pk_fma_f32 v[6:7], v[2:3], v[24:25], v[12:13]
	global_store_dwordx4 v[8:9], v[14:17], off
	global_store_dwordx4 v[8:9], v[4:7], off offset:16
	s_barrier
	s_cbranch_scc1 .LBB0_489

; #define MFMA32(a, b, c) __builtin_amdgcn_mfma_f32_32x32x16_bf16((a), (b), (c), 0, 0, 0)
; template <class Fin> __device__ __forceinline__ void ctx_gemm(const bf16_t* A, int lda, const bf16_t* Bt, int K, const Fin& fin, uchar* lds) {
;     ...
;     for (int id = blockIdx.x; id < 256; id += gridDim.x) {
;         const int tr = id >> 3, tc = id & 7;
;         const bf16_t* ap = A + (size_t)(tr * 32 + l32) * lda + wave * kw + 8 * hi;
;         const bf16_t* bp = Bt + (size_t)(tc * 128 + l32) * K + wave * kw + 8 * hi;
;         f32x16 acc0 = {}, acc1 = {}, acc2 = {}, acc3 = {};
; #pragma unroll 8
;         for (int s = 0; s < nst; ++s) {
;             const bf16x8 af = *(const bf16x8*)(ap + 16 * s);
;             const bf16x8 b0 = *(const bf16x8*)(bp + 16 * s), b1 = *(const bf16x8*)(bp + (size_t)32 * K + 16 * s), b2 = *(const bf16x8*)(bp + (size_t)64 * K + 16 * s), b3 = *(const bf16x8*)(bp + (size_t)96 * K + 16 * s);
;             acc0 = MFMA32(af, b0, acc0); acc1 = MFMA32(af, b1, acc1); acc2 = MFMA32(af, b2, acc2); acc3 = MFMA32(af, b3, acc3);
;         }
.LBB0_1310:
	s_and_b32 s8, s5, 0x380
	v_or_b32_e32 v0, s8, v80
	v_lshlrev_b32_e32 v0, 11, v0
	v_lshl_add_u64 v[76:77], v[68:69], 0, v[0:1]
	v_add_co_u32_e32 v74, vcc, s33, v76
	s_and_b32 s7, s4, 0xffffffe0
	s_nop 0
	v_addc_co_u32_e32 v75, vcc, 0, v77, vcc
	v_or_b32_e32 v2, s7, v80
	v_add_co_u32_e32 v72, vcc, s13, v76
	v_ashrrev_i32_e32 v3, 31, v2
	s_nop 0
	v_addc_co_u32_e32 v73, vcc, 0, v77, vcc
	v_lshlrev_b64 v[2:3], 11, v[2:3]
	v_add_co_u32_e32 v70, vcc, s22, v76
	v_lshl_add_u64 v[78:79], v[66:67], 0, v[2:3]
	s_nop 0
	v_addc_co_u32_e32 v71, vcc, 0, v77, vcc
	global_load_dwordx4 v[50:53], v[78:79], off
	global_load_dwordx4 v[2:5], v[76:77], off
	s_waitcnt lgkmcnt(0)
	global_load_dwordx4 v[18:21], v[74:75], off
	global_load_dwordx4 v[34:37], v[72:73], off
	global_load_dwordx4 v[54:57], v[70:71], off
	global_load_dwordx4 v[94:97], v[78:79], off offset:32
	global_load_dwordx4 v[98:101], v[76:77], off offset:32
	global_load_dwordx4 v[102:105], v[74:75], off offset:32
	global_load_dwordx4 v[106:109], v[72:73], off offset:32
	global_load_dwordx4 v[110:113], v[70:71], off offset:32
	v_add_u32_e32 v0, 0x400, v81
	s_add_i32 s6, s6, s90
	s_add_i32 s5, s5, s17
	s_add_i32 s4, s4, s64
	s_cmpk_lt_i32 s6, 0x100
	global_load_dwordx4 v[146:149], v[78:79], off offset:64
	global_load_dwordx4 v[150:153], v[76:77], off offset:64
	global_load_dwordx4 v[154:157], v[74:75], off offset:64
	global_load_dwordx4 v[158:161], v[72:73], off offset:64
	global_load_dwordx4 v[162:165], v[70:71], off offset:64
	global_load_dwordx4 v[166:169], v[78:79], off offset:96
	global_load_dwordx4 v[170:173], v[76:77], off offset:96
	global_load_dwordx4 v[174:177], v[74:75], off offset:96
	global_load_dwordx4 v[178:181], v[72:73], off offset:96
	global_load_dwordx4 v[182:185], v[70:71], off offset:96
	global_load_dwordx4 v[194:197], v[78:79], off offset:128
	global_load_dwordx4 v[198:201], v[76:77], off offset:128
	global_load_dwordx4 v[202:205], v[74:75], off offset:128
	global_load_dwordx4 v[220:223], v[72:73], off offset:128
	global_load_dwordx4 v[224:227], v[70:71], off offset:128
	s_waitcnt vmcnt(15)
	v_mfma_f32_32x32x16_bf16 v[2:17], v[50:53], v[2:5], 0
	v_mfma_f32_32x32x16_bf16 v[18:33], v[50:53], v[18:21], 0
	v_mfma_f32_32x32x16_bf16 v[34:49], v[50:53], v[34:37], 0
	v_mfma_f32_32x32x16_bf16 v[50:65], v[50:53], v[54:57], 0
	v_mfma_f32_32x32x16_bf16 v[2:17], v[94:97], v[98:101], v[2:17]
	v_mfma_f32_32x32x16_bf16 v[18:33], v[94:97], v[102:105], v[18:33]
	v_mfma_f32_32x32x16_bf16 v[34:49], v[94:97], v[106:109], v[34:49]
	v_mfma_f32_32x32x16_bf16 v[50:65], v[94:97], v[110:113], v[50:65]
	global_load_dwordx4 v[94:97], v[78:79], off offset:160
	global_load_dwordx4 v[98:101], v[76:77], off offset:160
	global_load_dwordx4 v[102:105], v[74:75], off offset:160
	global_load_dwordx4 v[106:109], v[72:73], off offset:160
	global_load_dwordx4 v[110:113], v[70:71], off offset:160
	s_waitcnt vmcnt(18)
	v_mfma_f32_32x32x16_bf16 v[2:17], v[146:149], v[150:153], v[2:17]
	s_waitcnt vmcnt(17)
	v_mfma_f32_32x32x16_bf16 v[18:33], v[146:149], v[154:157], v[18:33]
	s_waitcnt vmcnt(16)
	v_mfma_f32_32x32x16_bf16 v[34:49], v[146:149], v[158:161], v[34:49]
	s_waitcnt vmcnt(15)
	v_mfma_f32_32x32x16_bf16 v[50:65], v[146:149], v[162:165], v[50:65]
	global_load_dwordx4 v[146:149], v[78:79], off offset:192
	global_load_dwordx4 v[150:153], v[76:77], off offset:192
	global_load_dwordx4 v[154:157], v[74:75], off offset:192
	global_load_dwordx4 v[158:161], v[72:73], off offset:192
	global_load_dwordx4 v[162:165], v[70:71], off offset:192
	s_waitcnt vmcnt(18)
	v_mfma_f32_32x32x16_bf16 v[2:17], v[166:169], v[170:173], v[2:17]
	s_waitcnt vmcnt(17)
	v_mfma_f32_32x32x16_bf16 v[18:33], v[166:169], v[174:177], v[18:33]
	s_waitcnt vmcnt(16)
	v_mfma_f32_32x32x16_bf16 v[34:49], v[166:169], v[178:181], v[34:49]
	s_waitcnt vmcnt(15)
	v_mfma_f32_32x32x16_bf16 v[50:65], v[166:169], v[182:185], v[50:65]
	global_load_dwordx4 v[166:169], v[78:79], off offset:224
	global_load_dwordx4 v[170:173], v[76:77], off offset:224
	global_load_dwordx4 v[174:177], v[74:75], off offset:224
	global_load_dwordx4 v[178:181], v[72:73], off offset:224
	global_load_dwordx4 v[182:185], v[70:71], off offset:224
	s_waitcnt vmcnt(18)
	v_mfma_f32_32x32x16_bf16 v[2:17], v[194:197], v[198:201], v[2:17]
	s_waitcnt vmcnt(17)
	v_mfma_f32_32x32x16_bf16 v[18:33], v[194:197], v[202:205], v[18:33]
	s_waitcnt vmcnt(16)
	v_mfma_f32_32x32x16_bf16 v[34:49], v[194:197], v[220:223], v[34:49]
	s_waitcnt vmcnt(15)
	v_mfma_f32_32x32x16_bf16 v[50:65], v[194:197], v[224:227], v[50:65]
	s_waitcnt vmcnt(13)
	v_mfma_f32_32x32x16_bf16 v[2:17], v[94:97], v[98:101], v[2:17]
	s_waitcnt vmcnt(12)
	v_mfma_f32_32x32x16_bf16 v[18:33], v[94:97], v[102:105], v[18:33]
	s_waitcnt vmcnt(11)
	v_mfma_f32_32x32x16_bf16 v[34:49], v[94:97], v[106:109], v[34:49]
	s_waitcnt vmcnt(10)
	v_mfma_f32_32x32x16_bf16 v[50:65], v[94:97], v[110:113], v[50:65]
	s_waitcnt vmcnt(8)
	v_mfma_f32_32x32x16_bf16 v[2:17], v[146:149], v[150:153], v[2:17]
	s_waitcnt vmcnt(7)
	v_mfma_f32_32x32x16_bf16 v[18:33], v[146:149], v[154:157], v[18:33]
	s_waitcnt vmcnt(6)
	v_mfma_f32_32x32x16_bf16 v[34:49], v[146:149], v[158:161], v[34:49]
	s_waitcnt vmcnt(5)
	v_mfma_f32_32x32x16_bf16 v[50:65], v[146:149], v[162:165], v[50:65]
	s_waitcnt vmcnt(3)
	v_mfma_f32_32x32x16_bf16 v[2:17], v[166:169], v[170:173], v[2:17]
	s_waitcnt vmcnt(2)
	v_mfma_f32_32x32x16_bf16 v[18:33], v[166:169], v[174:177], v[18:33]
	s_waitcnt vmcnt(1)
	v_mfma_f32_32x32x16_bf16 v[34:49], v[166:169], v[178:181], v[34:49]
	s_waitcnt vmcnt(0)
; __device__ __forceinline__ int crow(int r, int hi) { return (r & 3) + 8 * (r >> 2) + 4 * hi; }
; #define MFMA32(a, b, c) __builtin_amdgcn_mfma_f32_32x32x16_bf16((a), (b), (c), 0, 0, 0)
; template <class Fin> __device__ __forceinline__ void ctx_gemm(const bf16_t* A, int lda, const bf16_t* Bt, int K, const Fin& fin, uchar* lds) {
;     ...
; #pragma unroll 8
;         for (int s = 0; s < nst; ++s) {
;             const bf16x8 af = *(const bf16x8*)(ap + 16 * s);
;             const bf16x8 b0 = *(const bf16x8*)(bp + 16 * s), b1 = *(const bf16x8*)(bp + (size_t)32 * K + 16 * s), b2 = *(const bf16x8*)(bp + (size_t)64 * K + 16 * s), b3 = *(const bf16x8*)(bp + (size_t)96 * K + 16 * s);
;             acc0 = MFMA32(af, b0, acc0); acc1 = MFMA32(af, b1, acc1); acc2 = MFMA32(af, b2, acc2); acc3 = MFMA32(af, b3, acc3);
;         }
;         float* rw = red + wave * 4096 + l32;
; #pragma unroll
;         for (int r = 0; r < 16; ++r) { float* q = rw + crow(r, hi) * 128; q[0] = acc0[r]; q[32] = acc1[r]; q[64] = acc2[r]; q[96] = acc3[r]; }
;         __syncthreads();
;         const int row = tid >> 4, c8 = (tid & 15) * 8;
;         f32x4 s0 = {}, s1 = {};
; #pragma unroll
;         for (int w = 0; w < 8; ++w) { s0 += *(const f32x4*)(red + w * 4096 + row * 128 + c8); s1 += *(const f32x4*)(red + w * 4096 + row * 128 + c8 + 4); }
;         fin(tr * 32 + row, tc * 128 + c8, s0, s1);
;         __syncthreads();
	v_mfma_f32_32x32x16_bf16 v[50:65], v[166:169], v[182:185], v[50:65]
	s_nop 7
	ds_write2_b32 v81, v2, v18 offset1:32
	s_nop 2
	ds_write2_b32 v81, v34, v50 offset0:64 offset1:96
	ds_write2_b32 v81, v3, v19 offset0:128 offset1:160
	ds_write2_b32 v81, v35, v51 offset0:192 offset1:224
	ds_write2_b32 v0, v4, v20 offset1:32
	ds_write2_b32 v0, v36, v52 offset0:64 offset1:96
	ds_write2_b32 v0, v5, v21 offset0:128 offset1:160
	ds_write2_b32 v0, v37, v53 offset0:192 offset1:224
	v_add_u32_e32 v0, 0x1000, v81
	ds_write2_b32 v0, v6, v22 offset1:32
	ds_write2_b32 v0, v38, v54 offset0:64 offset1:96
	ds_write2_b32 v0, v7, v23 offset0:128 offset1:160
	ds_write2_b32 v0, v39, v55 offset0:192 offset1:224
	v_add_u32_e32 v0, 0x1400, v81
	ds_write2_b32 v0, v8, v24 offset1:32
	ds_write2_b32 v0, v40, v56 offset0:64 offset1:96
	ds_write2_b32 v0, v9, v25 offset0:128 offset1:160
	ds_write2_b32 v0, v41, v57 offset0:192 offset1:224
	v_add_u32_e32 v0, 0x2000, v81
	ds_write2_b32 v0, v10, v26 offset1:32
	ds_write2_b32 v0, v42, v58 offset0:64 offset1:96
	ds_write2_b32 v0, v11, v27 offset0:128 offset1:160
	ds_write2_b32 v0, v43, v59 offset0:192 offset1:224
	v_add_u32_e32 v0, 0x2400, v81
	ds_write2_b32 v0, v12, v28 offset1:32
	ds_write2_b32 v0, v44, v60 offset0:64 offset1:96
	ds_write2_b32 v0, v13, v29 offset0:128 offset1:160
	ds_write2_b32 v0, v45, v61 offset0:192 offset1:224
	v_add_u32_e32 v0, 0x3000, v81
	ds_write2_b32 v0, v14, v30 offset1:32
	ds_write2_b32 v0, v46, v62 offset0:64 offset1:96
	ds_write2_b32 v0, v15, v31 offset0:128 offset1:160
	ds_write2_b32 v0, v47, v63 offset0:192 offset1:224
	v_add_u32_e32 v0, 0x3400, v81
	ds_write2_b32 v0, v16, v32 offset1:32
	ds_write2_b32 v0, v48, v64 offset0:64 offset1:96
	ds_write2_b32 v0, v17, v33 offset0:128 offset1:160
	ds_write2_b32 v0, v49, v65 offset0:192 offset1:224
	s_waitcnt lgkmcnt(0)
	s_barrier
	ds_read_b128 v[2:5], v84
	ds_read_b128 v[6:9], v84 offset:16
	v_add_u32_e32 v0, s7, v82
	s_waitcnt lgkmcnt(1)
	v_pk_add_f32 v[10:11], v[4:5], 0 op_sel_hi:[1,0]
	v_pk_add_f32 v[12:13], v[2:3], 0 op_sel_hi:[1,0]
	ds_read_b128 v[2:5], v84 offset:16384
	s_waitcnt lgkmcnt(1)
	v_pk_add_f32 v[8:9], v[8:9], 0 op_sel_hi:[1,0]
	v_pk_add_f32 v[6:7], v[6:7], 0 op_sel_hi:[1,0]
	s_waitcnt lgkmcnt(0)
	v_pk_add_f32 v[10:11], v[10:11], v[4:5]
	v_pk_add_f32 v[12:13], v[12:13], v[2:3]
	ds_read_b128 v[2:5], v84 offset:16400
	s_waitcnt lgkmcnt(0)
	v_pk_add_f32 v[8:9], v[8:9], v[4:5]
	v_pk_add_f32 v[6:7], v[6:7], v[2:3]
	ds_read_b128 v[2:5], v84 offset:32768
	s_waitcnt lgkmcnt(0)
	v_pk_add_f32 v[10:11], v[10:11], v[4:5]
	v_pk_add_f32 v[12:13], v[12:13], v[2:3]
	ds_read_b128 v[2:5], v84 offset:32784
	s_waitcnt lgkmcnt(0)
	v_pk_add_f32 v[8:9], v[8:9], v[4:5]
	v_pk_add_f32 v[6:7], v[6:7], v[2:3]
	ds_read_b128 v[2:5], v84 offset:49152
	s_waitcnt lgkmcnt(0)
	v_pk_add_f32 v[10:11], v[10:11], v[4:5]
	v_pk_add_f32 v[12:13], v[12:13], v[2:3]
	ds_read_b128 v[2:5], v84 offset:49168
	s_waitcnt lgkmcnt(0)
	v_pk_add_f32 v[8:9], v[8:9], v[4:5]
	v_pk_add_f32 v[6:7], v[6:7], v[2:3]
	ds_read_b128 v[2:5], v85
	s_waitcnt lgkmcnt(0)
	v_pk_add_f32 v[10:11], v[10:11], v[4:5]
	v_pk_add_f32 v[12:13], v[12:13], v[2:3]
	ds_read_b128 v[2:5], v86
	s_waitcnt lgkmcnt(0)
	v_pk_add_f32 v[8:9], v[8:9], v[4:5]
	v_pk_add_f32 v[6:7], v[6:7], v[2:3]
	ds_read_b128 v[2:5], v87
	s_waitcnt lgkmcnt(0)
	v_pk_add_f32 v[10:11], v[10:11], v[4:5]
	v_pk_add_f32 v[12:13], v[12:13], v[2:3]
	ds_read_b128 v[2:5], v88
	s_waitcnt lgkmcnt(0)
	v_pk_add_f32 v[8:9], v[8:9], v[4:5]
	v_pk_add_f32 v[6:7], v[6:7], v[2:3]
	ds_read_b128 v[2:5], v89
	s_waitcnt lgkmcnt(0)
	v_pk_add_f32 v[10:11], v[10:11], v[4:5]
	v_pk_add_f32 v[12:13], v[12:13], v[2:3]
	ds_read_b128 v[2:5], v90
	s_waitcnt lgkmcnt(0)
	v_pk_add_f32 v[14:15], v[8:9], v[4:5]
	v_pk_add_f32 v[16:17], v[6:7], v[2:3]
	ds_read_b128 v[2:5], v91
	s_waitcnt lgkmcnt(0)
	v_pk_add_f32 v[6:7], v[10:11], v[4:5]
	v_pk_add_f32 v[8:9], v[12:13], v[2:3]
	ds_read_b128 v[10:13], v92
	s_waitcnt lgkmcnt(0)
	v_pk_add_f32 v[2:3], v[14:15], v[12:13]
	v_pk_add_f32 v[4:5], v[16:17], v[10:11]
	v_or_b32_e32 v12, s8, v83
	v_mov_b64_e32 v[10:11], s[18:19]
	v_mad_i64_i32 v[10:11], s[8:9], v0, s16, v[10:11]
	v_lshlrev_b32_e32 v0, 1, v12
	v_lshl_add_u64 v[14:15], v[10:11], 0, v[0:1]
	global_load_dwordx4 v[10:13], v[14:15], off
	v_exp_f32_e64 v0, -v8
	s_waitcnt vmcnt(0)
	v_lshlrev_b32_e32 v18, 16, v10
	v_add_f32_e32 v0, 1.0, v0
	v_rcp_f32_e32 v16, v0
	v_exp_f32_e64 v0, -v9
	v_and_b32_e32 v19, 0xffff0000, v10
	v_lshlrev_b32_e32 v10, 16, v11
	v_and_b32_e32 v11, 0xffff0000, v11
	v_add_f32_e32 v0, 1.0, v0
	v_rcp_f32_e32 v17, v0
	v_exp_f32_e64 v0, -v6
	v_pk_mul_f32 v[8:9], v[8:9], v[16:17]
	v_add_f32_e32 v0, 1.0, v0
	v_rcp_f32_e32 v16, v0
	v_exp_f32_e64 v0, -v7
	v_pk_mul_f32 v[8:9], v[8:9], v[18:19]
	v_add_f32_e32 v0, 1.0, v0
	v_rcp_f32_e32 v17, v0
	v_exp_f32_e64 v0, -v4
	v_pk_mul_f32 v[6:7], v[6:7], v[16:17]
	v_add_f32_e32 v0, 1.0, v0
	v_pk_mul_f32 v[6:7], v[6:7], v[10:11]
	v_rcp_f32_e32 v10, v0
	v_exp_f32_e64 v0, -v5
	v_lshlrev_b32_e32 v16, 16, v12
	v_and_b32_e32 v17, 0xffff0000, v12
	v_lshlrev_b32_e32 v12, 16, v13
	v_add_f32_e32 v0, 1.0, v0
	v_rcp_f32_e32 v11, v0
	v_exp_f32_e64 v0, -v2
	v_and_b32_e32 v13, 0xffff0000, v13
	v_pk_mul_f32 v[4:5], v[4:5], v[10:11]
	v_add_f32_e32 v0, 1.0, v0
	v_rcp_f32_e32 v10, v0
	v_exp_f32_e64 v0, -v3
	v_pk_mul_f32 v[4:5], v[4:5], v[16:17]
	v_add_f32_e32 v0, 1.0, v0
	v_rcp_f32_e32 v11, v0
	v_cvt_pk_bf16_f32 v4, v4, v5
	v_pk_mul_f32 v[2:3], v[2:3], v[10:11]
	s_nop 0
	v_pk_mul_f32 v[10:11], v[2:3], v[12:13]
	v_cvt_pk_bf16_f32 v2, v8, v9
	v_cvt_pk_bf16_f32 v3, v6, v7
	v_cvt_pk_bf16_f32 v5, v10, v11
	global_store_dwordx4 v[14:15], v[2:5], off
	s_barrier
	s_cbranch_scc1 .LBB0_1310

; #define MFMA32(a, b, c) __builtin_amdgcn_mfma_f32_32x32x16_bf16((a), (b), (c), 0, 0, 0)
; template <class Fin> __device__ __forceinline__ void ctx_gemm(const bf16_t* A, int lda, const bf16_t* Bt, int K, const Fin& fin, uchar* lds) {
;     ...
;     for (int id = blockIdx.x; id < 256; id += gridDim.x) {
;         const int tr = id >> 3, tc = id & 7;
;         const bf16_t* ap = A + (size_t)(tr * 32 + l32) * lda + wave * kw + 8 * hi;
;         const bf16_t* bp = Bt + (size_t)(tc * 128 + l32) * K + wave * kw + 8 * hi;
;         f32x16 acc0 = {}, acc1 = {}, acc2 = {}, acc3 = {};
; #pragma unroll 8
;         for (int s = 0; s < nst; ++s) {
;             const bf16x8 af = *(const bf16x8*)(ap + 16 * s);
;             const bf16x8 b0 = *(const bf16x8*)(bp + 16 * s), b1 = *(const bf16x8*)(bp + (size_t)32 * K + 16 * s), b2 = *(const bf16x8*)(bp + (size_t)64 * K + 16 * s), b3 = *(const bf16x8*)(bp + (size_t)96 * K + 16 * s);
;             acc0 = MFMA32(af, b0, acc0); acc1 = MFMA32(af, b1, acc1); acc2 = MFMA32(af, b2, acc2); acc3 = MFMA32(af, b3, acc3);
;         }
.LBB0_1451:
	s_and_b32 s7, s4, 0xffffffe0
	v_or_b32_e32 v0, s7, v76
	v_mad_i64_i32 v[70:71], s[8:9], v0, s16, v[66:67]
	s_and_b32 s8, s5, 0x380
	s_nop 0
	v_or_b32_e32 v0, s8, v76
	v_lshlrev_b32_e32 v0, 11, v0
	v_lshl_add_u64 v[110:111], v[68:69], 0, v[0:1]
	v_add_co_u32_e32 v112, vcc, 0x10000, v110
	global_load_dwordx4 v[50:53], v[70:71], off
	global_load_dwordx4 v[2:5], v[110:111], off
	v_addc_co_u32_e32 v113, vcc, 0, v111, vcc
	v_add_co_u32_e32 v74, vcc, 0x20000, v110
	s_waitcnt lgkmcnt(0)
	global_load_dwordx4 v[18:21], v[112:113], off
	v_addc_co_u32_e32 v75, vcc, 0, v111, vcc
	v_add_co_u32_e32 v72, vcc, 0x30000, v110
	global_load_dwordx4 v[34:37], v[74:75], off
	s_nop 0
	v_addc_co_u32_e32 v73, vcc, 0, v111, vcc
	global_load_dwordx4 v[54:57], v[72:73], off
	global_load_dwordx4 v[90:93], v[70:71], off offset:32
	global_load_dwordx4 v[94:97], v[110:111], off offset:32
	global_load_dwordx4 v[98:101], v[112:113], off offset:32
	global_load_dwordx4 v[102:105], v[74:75], off offset:32
	global_load_dwordx4 v[106:109], v[72:73], off offset:32
	v_add_u32_e32 v0, 0x400, v77
	s_add_i32 s6, s6, s90
	s_add_i32 s5, s5, s17
	s_add_i32 s4, s4, s64
	s_cmpk_lt_i32 s6, 0x100
	global_load_dwordx4 v[146:149], v[70:71], off offset:64
	global_load_dwordx4 v[150:153], v[110:111], off offset:64
	global_load_dwordx4 v[154:157], v[112:113], off offset:64
	global_load_dwordx4 v[158:161], v[74:75], off offset:64
	global_load_dwordx4 v[162:165], v[72:73], off offset:64
	global_load_dwordx4 v[166:169], v[70:71], off offset:96
	global_load_dwordx4 v[170:173], v[110:111], off offset:96
	global_load_dwordx4 v[174:177], v[112:113], off offset:96
	global_load_dwordx4 v[178:181], v[74:75], off offset:96
	global_load_dwordx4 v[182:185], v[72:73], off offset:96
	global_load_dwordx4 v[194:197], v[70:71], off offset:128
	global_load_dwordx4 v[198:201], v[110:111], off offset:128
	global_load_dwordx4 v[202:205], v[112:113], off offset:128
	global_load_dwordx4 v[220:223], v[74:75], off offset:128
	global_load_dwordx4 v[224:227], v[72:73], off offset:128
	s_waitcnt vmcnt(15)
	v_mfma_f32_32x32x16_bf16 v[2:17], v[50:53], v[2:5], 0
	v_mfma_f32_32x32x16_bf16 v[18:33], v[50:53], v[18:21], 0
	v_mfma_f32_32x32x16_bf16 v[34:49], v[50:53], v[34:37], 0
	v_mfma_f32_32x32x16_bf16 v[50:65], v[50:53], v[54:57], 0
	v_mfma_f32_32x32x16_bf16 v[2:17], v[90:93], v[94:97], v[2:17]
	v_mfma_f32_32x32x16_bf16 v[18:33], v[90:93], v[98:101], v[18:33]
	v_mfma_f32_32x32x16_bf16 v[34:49], v[90:93], v[102:105], v[34:49]
	v_mfma_f32_32x32x16_bf16 v[50:65], v[90:93], v[106:109], v[50:65]
	global_load_dwordx4 v[90:93], v[70:71], off offset:160
	global_load_dwordx4 v[94:97], v[110:111], off offset:160
	global_load_dwordx4 v[98:101], v[112:113], off offset:160
	global_load_dwordx4 v[102:105], v[74:75], off offset:160
	global_load_dwordx4 v[106:109], v[72:73], off offset:160
	s_waitcnt vmcnt(18)
	v_mfma_f32_32x32x16_bf16 v[2:17], v[146:149], v[150:153], v[2:17]
	s_waitcnt vmcnt(17)
	v_mfma_f32_32x32x16_bf16 v[18:33], v[146:149], v[154:157], v[18:33]
	s_waitcnt vmcnt(16)
	v_mfma_f32_32x32x16_bf16 v[34:49], v[146:149], v[158:161], v[34:49]
	s_waitcnt vmcnt(15)
	v_mfma_f32_32x32x16_bf16 v[50:65], v[146:149], v[162:165], v[50:65]
	global_load_dwordx4 v[146:149], v[70:71], off offset:192
	global_load_dwordx4 v[150:153], v[110:111], off offset:192
	global_load_dwordx4 v[154:157], v[112:113], off offset:192
	global_load_dwordx4 v[158:161], v[74:75], off offset:192
	global_load_dwordx4 v[162:165], v[72:73], off offset:192
	s_waitcnt vmcnt(18)
	v_mfma_f32_32x32x16_bf16 v[2:17], v[166:169], v[170:173], v[2:17]
	s_waitcnt vmcnt(17)
	v_mfma_f32_32x32x16_bf16 v[18:33], v[166:169], v[174:177], v[18:33]
	s_waitcnt vmcnt(16)
	v_mfma_f32_32x32x16_bf16 v[34:49], v[166:169], v[178:181], v[34:49]
	s_waitcnt vmcnt(15)
	v_mfma_f32_32x32x16_bf16 v[50:65], v[166:169], v[182:185], v[50:65]
	global_load_dwordx4 v[166:169], v[70:71], off offset:224
	global_load_dwordx4 v[170:173], v[110:111], off offset:224
	global_load_dwordx4 v[174:177], v[112:113], off offset:224
	global_load_dwordx4 v[178:181], v[74:75], off offset:224
	global_load_dwordx4 v[182:185], v[72:73], off offset:224
	s_waitcnt vmcnt(18)
	v_mfma_f32_32x32x16_bf16 v[2:17], v[194:197], v[198:201], v[2:17]
	s_waitcnt vmcnt(17)
	v_mfma_f32_32x32x16_bf16 v[18:33], v[194:197], v[202:205], v[18:33]
	s_waitcnt vmcnt(16)
	v_mfma_f32_32x32x16_bf16 v[34:49], v[194:197], v[220:223], v[34:49]
	s_waitcnt vmcnt(15)
	v_mfma_f32_32x32x16_bf16 v[50:65], v[194:197], v[224:227], v[50:65]
	s_waitcnt vmcnt(13)
	v_mfma_f32_32x32x16_bf16 v[2:17], v[90:93], v[94:97], v[2:17]
	s_waitcnt vmcnt(12)
	v_mfma_f32_32x32x16_bf16 v[18:33], v[90:93], v[98:101], v[18:33]
	s_waitcnt vmcnt(11)
	v_mfma_f32_32x32x16_bf16 v[34:49], v[90:93], v[102:105], v[34:49]
	s_waitcnt vmcnt(10)
	v_mfma_f32_32x32x16_bf16 v[50:65], v[90:93], v[106:109], v[50:65]
	s_waitcnt vmcnt(8)
	v_mfma_f32_32x32x16_bf16 v[2:17], v[146:149], v[150:153], v[2:17]
	s_waitcnt vmcnt(7)
; __device__ __forceinline__ int crow(int r, int hi) { return (r & 3) + 8 * (r >> 2) + 4 * hi; }
; #define MFMA32(a, b, c) __builtin_amdgcn_mfma_f32_32x32x16_bf16((a), (b), (c), 0, 0, 0)
; template <class Fin> __device__ __forceinline__ void ctx_gemm(const bf16_t* A, int lda, const bf16_t* Bt, int K, const Fin& fin, uchar* lds) {
;     ...
;             acc0 = MFMA32(af, b0, acc0); acc1 = MFMA32(af, b1, acc1); acc2 = MFMA32(af, b2, acc2); acc3 = MFMA32(af, b3, acc3);
;         }
;         float* rw = red + wave * 4096 + l32;
; #pragma unroll
;         for (int r = 0; r < 16; ++r) { float* q = rw + crow(r, hi) * 128; q[0] = acc0[r]; q[32] = acc1[r]; q[64] = acc2[r]; q[96] = acc3[r]; }
;         __syncthreads();
;         const int row = tid >> 4, c8 = (tid & 15) * 8;
;         f32x4 s0 = {}, s1 = {};
; #pragma unroll
;         for (int w = 0; w < 8; ++w) { s0 += *(const f32x4*)(red + w * 4096 + row * 128 + c8); s1 += *(const f32x4*)(red + w * 4096 + row * 128 + c8 + 4); }
;         fin(tr * 32 + row, tc * 128 + c8, s0, s1);
	v_mfma_f32_32x32x16_bf16 v[18:33], v[146:149], v[154:157], v[18:33]
	s_waitcnt vmcnt(6)
	v_mfma_f32_32x32x16_bf16 v[34:49], v[146:149], v[158:161], v[34:49]
	s_waitcnt vmcnt(5)
	v_mfma_f32_32x32x16_bf16 v[50:65], v[146:149], v[162:165], v[50:65]
	s_waitcnt vmcnt(3)
	v_mfma_f32_32x32x16_bf16 v[2:17], v[166:169], v[170:173], v[2:17]
	s_waitcnt vmcnt(2)
	v_mfma_f32_32x32x16_bf16 v[18:33], v[166:169], v[174:177], v[18:33]
	s_waitcnt vmcnt(1)
	v_mfma_f32_32x32x16_bf16 v[34:49], v[166:169], v[178:181], v[34:49]
	s_waitcnt vmcnt(0)
	v_mfma_f32_32x32x16_bf16 v[50:65], v[166:169], v[182:185], v[50:65]
	s_nop 7
	ds_write2_b32 v77, v2, v18 offset1:32
	s_nop 2
	ds_write2_b32 v77, v34, v50 offset0:64 offset1:96
	ds_write2_b32 v77, v3, v19 offset0:128 offset1:160
	ds_write2_b32 v77, v35, v51 offset0:192 offset1:224
	ds_write2_b32 v0, v4, v20 offset1:32
	ds_write2_b32 v0, v36, v52 offset0:64 offset1:96
	ds_write2_b32 v0, v5, v21 offset0:128 offset1:160
	ds_write2_b32 v0, v37, v53 offset0:192 offset1:224
	v_add_u32_e32 v0, 0x1000, v77
	ds_write2_b32 v0, v6, v22 offset1:32
	ds_write2_b32 v0, v38, v54 offset0:64 offset1:96
	ds_write2_b32 v0, v7, v23 offset0:128 offset1:160
	ds_write2_b32 v0, v39, v55 offset0:192 offset1:224
	v_add_u32_e32 v0, 0x1400, v77
	ds_write2_b32 v0, v8, v24 offset1:32
	ds_write2_b32 v0, v40, v56 offset0:64 offset1:96
	ds_write2_b32 v0, v9, v25 offset0:128 offset1:160
	ds_write2_b32 v0, v41, v57 offset0:192 offset1:224
	v_add_u32_e32 v0, 0x2000, v77
	ds_write2_b32 v0, v10, v26 offset1:32
	ds_write2_b32 v0, v42, v58 offset0:64 offset1:96
	ds_write2_b32 v0, v11, v27 offset0:128 offset1:160
	ds_write2_b32 v0, v43, v59 offset0:192 offset1:224
	v_add_u32_e32 v0, 0x2400, v77
	ds_write2_b32 v0, v12, v28 offset1:32
	ds_write2_b32 v0, v44, v60 offset0:64 offset1:96
	ds_write2_b32 v0, v13, v29 offset0:128 offset1:160
	ds_write2_b32 v0, v45, v61 offset0:192 offset1:224
	v_add_u32_e32 v0, 0x3000, v77
	ds_write2_b32 v0, v14, v30 offset1:32
	ds_write2_b32 v0, v46, v62 offset0:64 offset1:96
	ds_write2_b32 v0, v15, v31 offset0:128 offset1:160
	ds_write2_b32 v0, v47, v63 offset0:192 offset1:224
	v_add_u32_e32 v0, 0x3400, v77
	ds_write2_b32 v0, v16, v32 offset1:32
	ds_write2_b32 v0, v48, v64 offset0:64 offset1:96
	ds_write2_b32 v0, v17, v33 offset0:128 offset1:160
	ds_write2_b32 v0, v49, v65 offset0:192 offset1:224
	s_waitcnt lgkmcnt(0)
	s_barrier
	ds_read_b128 v[2:5], v80
	ds_read_b128 v[6:9], v80 offset:16
	v_add_u32_e32 v0, s7, v78
	s_waitcnt lgkmcnt(1)
	v_pk_add_f32 v[10:11], v[4:5], 0 op_sel_hi:[1,0]
	v_pk_add_f32 v[12:13], v[2:3], 0 op_sel_hi:[1,0]
	ds_read_b128 v[2:5], v80 offset:16384
	s_waitcnt lgkmcnt(1)
	v_pk_add_f32 v[8:9], v[8:9], 0 op_sel_hi:[1,0]
	v_pk_add_f32 v[6:7], v[6:7], 0 op_sel_hi:[1,0]
	s_waitcnt lgkmcnt(0)
	v_pk_add_f32 v[10:11], v[10:11], v[4:5]
	v_pk_add_f32 v[12:13], v[12:13], v[2:3]
	ds_read_b128 v[2:5], v80 offset:16400
	s_waitcnt lgkmcnt(0)
	v_pk_add_f32 v[8:9], v[8:9], v[4:5]
	v_pk_add_f32 v[6:7], v[6:7], v[2:3]
	ds_read_b128 v[2:5], v80 offset:32768
	s_waitcnt lgkmcnt(0)
	v_pk_add_f32 v[10:11], v[10:11], v[4:5]
	v_pk_add_f32 v[12:13], v[12:13], v[2:3]
	ds_read_b128 v[2:5], v80 offset:32784
	s_waitcnt lgkmcnt(0)
	v_pk_add_f32 v[8:9], v[8:9], v[4:5]
	v_pk_add_f32 v[6:7], v[6:7], v[2:3]
	ds_read_b128 v[2:5], v80 offset:49152
	s_waitcnt lgkmcnt(0)
	v_pk_add_f32 v[10:11], v[10:11], v[4:5]
	v_pk_add_f32 v[12:13], v[12:13], v[2:3]
	ds_read_b128 v[2:5], v80 offset:49168
	s_waitcnt lgkmcnt(0)
	v_pk_add_f32 v[8:9], v[8:9], v[4:5]
	v_pk_add_f32 v[6:7], v[6:7], v[2:3]
	ds_read_b128 v[2:5], v81
	s_waitcnt lgkmcnt(0)
	v_pk_add_f32 v[10:11], v[10:11], v[4:5]
	v_pk_add_f32 v[12:13], v[12:13], v[2:3]
	ds_read_b128 v[2:5], v82
	s_waitcnt lgkmcnt(0)
	v_pk_add_f32 v[8:9], v[8:9], v[4:5]
	v_pk_add_f32 v[6:7], v[6:7], v[2:3]
	ds_read_b128 v[2:5], v83
	s_waitcnt lgkmcnt(0)
	v_pk_add_f32 v[10:11], v[10:11], v[4:5]
	v_pk_add_f32 v[12:13], v[12:13], v[2:3]
	ds_read_b128 v[2:5], v84
	s_waitcnt lgkmcnt(0)
	v_pk_add_f32 v[8:9], v[8:9], v[4:5]
	v_pk_add_f32 v[6:7], v[6:7], v[2:3]
	ds_read_b128 v[2:5], v85
	s_waitcnt lgkmcnt(0)
	v_pk_add_f32 v[10:11], v[10:11], v[4:5]
	v_pk_add_f32 v[12:13], v[12:13], v[2:3]
	ds_read_b128 v[2:5], v86
	s_waitcnt lgkmcnt(0)
	v_pk_add_f32 v[14:15], v[8:9], v[4:5]
	v_pk_add_f32 v[16:17], v[6:7], v[2:3]
	ds_read_b128 v[4:7], v87
	s_waitcnt lgkmcnt(0)
	v_pk_add_f32 v[2:3], v[10:11], v[6:7]
	ds_read_b128 v[8:11], v88
	v_pk_add_f32 v[6:7], v[12:13], v[4:5]
	v_or_b32_e32 v12, s8, v79
	v_cvt_pk_bf16_f32 v6, v6, v7
	v_cvt_pk_bf16_f32 v7, v2, v3
	s_waitcnt lgkmcnt(0)
	v_pk_add_f32 v[4:5], v[14:15], v[10:11]
	v_mov_b64_e32 v[10:11], s[60:61]
	v_pk_add_f32 v[8:9], v[16:17], v[8:9]
	v_mad_i64_i32 v[10:11], s[8:9], v0, s16, v[10:11]
	v_lshlrev_b32_e32 v0, 1, v12
	v_lshl_add_u64 v[10:11], v[10:11], 0, v[0:1]
	v_cvt_pk_bf16_f32 v8, v8, v9
	v_cvt_pk_bf16_f32 v9, v4, v5
	global_store_dwordx4 v[10:11], v[6:9], off
	s_barrier
	s_cbranch_scc1 .LBB0_1451

; #define MFMA32(a, b, c) __builtin_amdgcn_mfma_f32_32x32x16_bf16((a), (b), (c), 0, 0, 0)
; template <class Fin> __device__ __forceinline__ void ctx_gemm(const bf16_t* A, int lda, const bf16_t* Bt, int K, const Fin& fin, uchar* lds) {
;     ...
;     for (int id = blockIdx.x; id < 256; id += gridDim.x) {
;         const int tr = id >> 3, tc = id & 7;
;         const bf16_t* ap = A + (size_t)(tr * 32 + l32) * lda + wave * kw + 8 * hi;
;         const bf16_t* bp = Bt + (size_t)(tc * 128 + l32) * K + wave * kw + 8 * hi;
;         f32x16 acc0 = {}, acc1 = {}, acc2 = {}, acc3 = {};
; #pragma unroll 8
;         for (int s = 0; s < nst; ++s) {
;             const bf16x8 af = *(const bf16x8*)(ap + 16 * s);
;             const bf16x8 b0 = *(const bf16x8*)(bp + 16 * s), b1 = *(const bf16x8*)(bp + (size_t)32 * K + 16 * s), b2 = *(const bf16x8*)(bp + (size_t)64 * K + 16 * s), b3 = *(const bf16x8*)(bp + (size_t)96 * K + 16 * s);
;             acc0 = MFMA32(af, b0, acc0); acc1 = MFMA32(af, b1, acc1); acc2 = MFMA32(af, b2, acc2); acc3 = MFMA32(af, b3, acc3);
.LBB0_1454:
	s_and_b32 s8, s5, 0x380
	v_or_b32_e32 v0, s8, v80
	v_lshlrev_b32_e32 v0, 11, v0
	v_lshl_add_u64 v[76:77], v[68:69], 0, v[0:1]
	v_add_co_u32_e32 v74, vcc, s33, v76
	s_and_b32 s7, s4, 0xffffffe0
	s_nop 0
	v_addc_co_u32_e32 v75, vcc, 0, v77, vcc
	v_or_b32_e32 v2, s7, v80
	v_add_co_u32_e32 v72, vcc, s13, v76
	v_ashrrev_i32_e32 v3, 31, v2
	s_nop 0
	v_addc_co_u32_e32 v73, vcc, 0, v77, vcc
	v_lshlrev_b64 v[2:3], 11, v[2:3]
	v_add_co_u32_e32 v70, vcc, s18, v76
	v_lshl_add_u64 v[78:79], v[66:67], 0, v[2:3]
	s_nop 0
	v_addc_co_u32_e32 v71, vcc, 0, v77, vcc
	global_load_dwordx4 v[50:53], v[78:79], off
	global_load_dwordx4 v[2:5], v[76:77], off
	s_waitcnt lgkmcnt(0)
	global_load_dwordx4 v[18:21], v[74:75], off
	global_load_dwordx4 v[34:37], v[72:73], off
	global_load_dwordx4 v[54:57], v[70:71], off
	global_load_dwordx4 v[94:97], v[78:79], off offset:32
	global_load_dwordx4 v[98:101], v[76:77], off offset:32
	global_load_dwordx4 v[102:105], v[74:75], off offset:32
	global_load_dwordx4 v[106:109], v[72:73], off offset:32
	global_load_dwordx4 v[110:113], v[70:71], off offset:32
	v_add_u32_e32 v0, 0x400, v81
	s_add_i32 s6, s6, s90
	s_add_i32 s5, s5, s17
	s_add_i32 s4, s4, s64
	s_cmpk_lt_i32 s6, 0x100
	global_load_dwordx4 v[146:149], v[78:79], off offset:64
	global_load_dwordx4 v[150:153], v[76:77], off offset:64
	global_load_dwordx4 v[154:157], v[74:75], off offset:64
	global_load_dwordx4 v[158:161], v[72:73], off offset:64
	global_load_dwordx4 v[162:165], v[70:71], off offset:64
	global_load_dwordx4 v[166:169], v[78:79], off offset:96
	global_load_dwordx4 v[170:173], v[76:77], off offset:96
	global_load_dwordx4 v[174:177], v[74:75], off offset:96
	global_load_dwordx4 v[178:181], v[72:73], off offset:96
	global_load_dwordx4 v[182:185], v[70:71], off offset:96
	global_load_dwordx4 v[194:197], v[78:79], off offset:128
	global_load_dwordx4 v[198:201], v[76:77], off offset:128
	global_load_dwordx4 v[202:205], v[74:75], off offset:128
	global_load_dwordx4 v[220:223], v[72:73], off offset:128
	global_load_dwordx4 v[224:227], v[70:71], off offset:128
	s_waitcnt vmcnt(15)
	v_mfma_f32_32x32x16_bf16 v[2:17], v[50:53], v[2:5], 0
	v_mfma_f32_32x32x16_bf16 v[18:33], v[50:53], v[18:21], 0
	v_mfma_f32_32x32x16_bf16 v[34:49], v[50:53], v[34:37], 0
	v_mfma_f32_32x32x16_bf16 v[50:65], v[50:53], v[54:57], 0
	v_mfma_f32_32x32x16_bf16 v[2:17], v[94:97], v[98:101], v[2:17]
	v_mfma_f32_32x32x16_bf16 v[18:33], v[94:97], v[102:105], v[18:33]
	v_mfma_f32_32x32x16_bf16 v[34:49], v[94:97], v[106:109], v[34:49]
	v_mfma_f32_32x32x16_bf16 v[50:65], v[94:97], v[110:113], v[50:65]
	global_load_dwordx4 v[94:97], v[78:79], off offset:160
	global_load_dwordx4 v[98:101], v[76:77], off offset:160
	global_load_dwordx4 v[102:105], v[74:75], off offset:160
	global_load_dwordx4 v[106:109], v[72:73], off offset:160
	global_load_dwordx4 v[110:113], v[70:71], off offset:160
	s_waitcnt vmcnt(18)
	v_mfma_f32_32x32x16_bf16 v[2:17], v[146:149], v[150:153], v[2:17]
	s_waitcnt vmcnt(17)
	v_mfma_f32_32x32x16_bf16 v[18:33], v[146:149], v[154:157], v[18:33]
	s_waitcnt vmcnt(16)
	v_mfma_f32_32x32x16_bf16 v[34:49], v[146:149], v[158:161], v[34:49]
	s_waitcnt vmcnt(15)
	v_mfma_f32_32x32x16_bf16 v[50:65], v[146:149], v[162:165], v[50:65]
	global_load_dwordx4 v[146:149], v[78:79], off offset:192
	global_load_dwordx4 v[150:153], v[76:77], off offset:192
	global_load_dwordx4 v[154:157], v[74:75], off offset:192
	global_load_dwordx4 v[158:161], v[72:73], off offset:192
	global_load_dwordx4 v[162:165], v[70:71], off offset:192
	s_waitcnt vmcnt(18)
	v_mfma_f32_32x32x16_bf16 v[2:17], v[166:169], v[170:173], v[2:17]
	s_waitcnt vmcnt(17)
	v_mfma_f32_32x32x16_bf16 v[18:33], v[166:169], v[174:177], v[18:33]
	s_waitcnt vmcnt(16)
	v_mfma_f32_32x32x16_bf16 v[34:49], v[166:169], v[178:181], v[34:49]
	s_waitcnt vmcnt(15)
	v_mfma_f32_32x32x16_bf16 v[50:65], v[166:169], v[182:185], v[50:65]
	global_load_dwordx4 v[166:169], v[78:79], off offset:224
	global_load_dwordx4 v[170:173], v[76:77], off offset:224
	global_load_dwordx4 v[174:177], v[74:75], off offset:224
	global_load_dwordx4 v[178:181], v[72:73], off offset:224
	global_load_dwordx4 v[182:185], v[70:71], off offset:224
	s_waitcnt vmcnt(18)
	v_mfma_f32_32x32x16_bf16 v[2:17], v[194:197], v[198:201], v[2:17]
	s_waitcnt vmcnt(17)
	v_mfma_f32_32x32x16_bf16 v[18:33], v[194:197], v[202:205], v[18:33]
	s_waitcnt vmcnt(16)
	v_mfma_f32_32x32x16_bf16 v[34:49], v[194:197], v[220:223], v[34:49]
	s_waitcnt vmcnt(15)
	v_mfma_f32_32x32x16_bf16 v[50:65], v[194:197], v[224:227], v[50:65]
	s_waitcnt vmcnt(13)
	v_mfma_f32_32x32x16_bf16 v[2:17], v[94:97], v[98:101], v[2:17]
	s_waitcnt vmcnt(12)
	v_mfma_f32_32x32x16_bf16 v[18:33], v[94:97], v[102:105], v[18:33]
	s_waitcnt vmcnt(11)
	v_mfma_f32_32x32x16_bf16 v[34:49], v[94:97], v[106:109], v[34:49]
	s_waitcnt vmcnt(10)
	v_mfma_f32_32x32x16_bf16 v[50:65], v[94:97], v[110:113], v[50:65]
	s_waitcnt vmcnt(8)
	v_mfma_f32_32x32x16_bf16 v[2:17], v[146:149], v[150:153], v[2:17]
	s_waitcnt vmcnt(7)
	v_mfma_f32_32x32x16_bf16 v[18:33], v[146:149], v[154:157], v[18:33]
	s_waitcnt vmcnt(6)
	v_mfma_f32_32x32x16_bf16 v[34:49], v[146:149], v[158:161], v[34:49]
	s_waitcnt vmcnt(5)
	v_mfma_f32_32x32x16_bf16 v[50:65], v[146:149], v[162:165], v[50:65]
	s_waitcnt vmcnt(3)
	v_mfma_f32_32x32x16_bf16 v[2:17], v[166:169], v[170:173], v[2:17]
	s_waitcnt vmcnt(2)
	v_mfma_f32_32x32x16_bf16 v[18:33], v[166:169], v[174:177], v[18:33]
	s_waitcnt vmcnt(1)
	v_mfma_f32_32x32x16_bf16 v[34:49], v[166:169], v[178:181], v[34:49]
	s_waitcnt vmcnt(0)
; __device__ __forceinline__ int crow(int r, int hi) { return (r & 3) + 8 * (r >> 2) + 4 * hi; }
; #define MFMA32(a, b, c) __builtin_amdgcn_mfma_f32_32x32x16_bf16((a), (b), (c), 0, 0, 0)
; template <class Fin> __device__ __forceinline__ void ctx_gemm(const bf16_t* A, int lda, const bf16_t* Bt, int K, const Fin& fin, uchar* lds) {
;     ...
;             acc0 = MFMA32(af, b0, acc0); acc1 = MFMA32(af, b1, acc1); acc2 = MFMA32(af, b2, acc2); acc3 = MFMA32(af, b3, acc3);
;         }
;         float* rw = red + wave * 4096 + l32;
; #pragma unroll
;         for (int r = 0; r < 16; ++r) { float* q = rw + crow(r, hi) * 128; q[0] = acc0[r]; q[32] = acc1[r]; q[64] = acc2[r]; q[96] = acc3[r]; }
;         __syncthreads();
;         const int row = tid >> 4, c8 = (tid & 15) * 8;
;         f32x4 s0 = {}, s1 = {};
; #pragma unroll
;         for (int w = 0; w < 8; ++w) { s0 += *(const f32x4*)(red + w * 4096 + row * 128 + c8); s1 += *(const f32x4*)(red + w * 4096 + row * 128 + c8 + 4); }
;         fin(tr * 32 + row, tc * 128 + c8, s0, s1);
	v_mfma_f32_32x32x16_bf16 v[50:65], v[166:169], v[182:185], v[50:65]
	s_nop 7
	ds_write2_b32 v81, v2, v18 offset1:32
	s_nop 2
	ds_write2_b32 v81, v34, v50 offset0:64 offset1:96
	ds_write2_b32 v81, v3, v19 offset0:128 offset1:160
	ds_write2_b32 v81, v35, v51 offset0:192 offset1:224
	ds_write2_b32 v0, v4, v20 offset1:32
	ds_write2_b32 v0, v36, v52 offset0:64 offset1:96
	ds_write2_b32 v0, v5, v21 offset0:128 offset1:160
	ds_write2_b32 v0, v37, v53 offset0:192 offset1:224
	v_add_u32_e32 v0, 0x1000, v81
	ds_write2_b32 v0, v6, v22 offset1:32
	ds_write2_b32 v0, v38, v54 offset0:64 offset1:96
	ds_write2_b32 v0, v7, v23 offset0:128 offset1:160
	ds_write2_b32 v0, v39, v55 offset0:192 offset1:224
	v_add_u32_e32 v0, 0x1400, v81
	ds_write2_b32 v0, v8, v24 offset1:32
	ds_write2_b32 v0, v40, v56 offset0:64 offset1:96
	ds_write2_b32 v0, v9, v25 offset0:128 offset1:160
	ds_write2_b32 v0, v41, v57 offset0:192 offset1:224
	v_add_u32_e32 v0, 0x2000, v81
	ds_write2_b32 v0, v10, v26 offset1:32
	ds_write2_b32 v0, v42, v58 offset0:64 offset1:96
	ds_write2_b32 v0, v11, v27 offset0:128 offset1:160
	ds_write2_b32 v0, v43, v59 offset0:192 offset1:224
	v_add_u32_e32 v0, 0x2400, v81
	ds_write2_b32 v0, v12, v28 offset1:32
	ds_write2_b32 v0, v44, v60 offset0:64 offset1:96
	ds_write2_b32 v0, v13, v29 offset0:128 offset1:160
	ds_write2_b32 v0, v45, v61 offset0:192 offset1:224
	v_add_u32_e32 v0, 0x3000, v81
	ds_write2_b32 v0, v14, v30 offset1:32
	ds_write2_b32 v0, v46, v62 offset0:64 offset1:96
	ds_write2_b32 v0, v15, v31 offset0:128 offset1:160
	ds_write2_b32 v0, v47, v63 offset0:192 offset1:224
	v_add_u32_e32 v0, 0x3400, v81
	ds_write2_b32 v0, v16, v32 offset1:32
	ds_write2_b32 v0, v48, v64 offset0:64 offset1:96
	ds_write2_b32 v0, v17, v33 offset0:128 offset1:160
	ds_write2_b32 v0, v49, v65 offset0:192 offset1:224
	s_waitcnt lgkmcnt(0)
	s_barrier
	ds_read_b128 v[2:5], v84
	ds_read_b128 v[6:9], v84 offset:16
	v_add_u32_e32 v0, s7, v82
	s_waitcnt lgkmcnt(1)
	v_pk_add_f32 v[10:11], v[4:5], 0 op_sel_hi:[1,0]
	v_pk_add_f32 v[12:13], v[2:3], 0 op_sel_hi:[1,0]
	ds_read_b128 v[2:5], v84 offset:16384
	s_waitcnt lgkmcnt(1)
	v_pk_add_f32 v[8:9], v[8:9], 0 op_sel_hi:[1,0]
	v_pk_add_f32 v[6:7], v[6:7], 0 op_sel_hi:[1,0]
	s_waitcnt lgkmcnt(0)
	v_pk_add_f32 v[10:11], v[10:11], v[4:5]
	v_pk_add_f32 v[12:13], v[12:13], v[2:3]
	ds_read_b128 v[2:5], v84 offset:16400
	s_waitcnt lgkmcnt(0)
	v_pk_add_f32 v[8:9], v[8:9], v[4:5]
	v_pk_add_f32 v[6:7], v[6:7], v[2:3]
	ds_read_b128 v[2:5], v84 offset:32768
	s_waitcnt lgkmcnt(0)
	v_pk_add_f32 v[10:11], v[10:11], v[4:5]
	v_pk_add_f32 v[12:13], v[12:13], v[2:3]
	ds_read_b128 v[2:5], v84 offset:32784
	s_waitcnt lgkmcnt(0)
	v_pk_add_f32 v[8:9], v[8:9], v[4:5]
	v_pk_add_f32 v[6:7], v[6:7], v[2:3]
	ds_read_b128 v[2:5], v84 offset:49152
	s_waitcnt lgkmcnt(0)
	v_pk_add_f32 v[10:11], v[10:11], v[4:5]
	v_pk_add_f32 v[12:13], v[12:13], v[2:3]
	ds_read_b128 v[2:5], v84 offset:49168
	s_waitcnt lgkmcnt(0)
	v_pk_add_f32 v[8:9], v[8:9], v[4:5]
	v_pk_add_f32 v[6:7], v[6:7], v[2:3]
	ds_read_b128 v[2:5], v85
	s_waitcnt lgkmcnt(0)
	v_pk_add_f32 v[10:11], v[10:11], v[4:5]
	v_pk_add_f32 v[12:13], v[12:13], v[2:3]
	ds_read_b128 v[2:5], v86
	s_waitcnt lgkmcnt(0)
	v_pk_add_f32 v[8:9], v[8:9], v[4:5]
	v_pk_add_f32 v[6:7], v[6:7], v[2:3]
	ds_read_b128 v[2:5], v87
	s_waitcnt lgkmcnt(0)
	v_pk_add_f32 v[10:11], v[10:11], v[4:5]
	v_pk_add_f32 v[12:13], v[12:13], v[2:3]
	ds_read_b128 v[2:5], v88
	s_waitcnt lgkmcnt(0)
	v_pk_add_f32 v[8:9], v[8:9], v[4:5]
	v_pk_add_f32 v[6:7], v[6:7], v[2:3]
	ds_read_b128 v[2:5], v89
	s_waitcnt lgkmcnt(0)
	v_pk_add_f32 v[10:11], v[10:11], v[4:5]
	v_pk_add_f32 v[12:13], v[12:13], v[2:3]
	ds_read_b128 v[2:5], v90
	s_waitcnt lgkmcnt(0)
	v_pk_add_f32 v[14:15], v[8:9], v[4:5]
	v_pk_add_f32 v[16:17], v[6:7], v[2:3]
	ds_read_b128 v[2:5], v91
	s_waitcnt lgkmcnt(0)
	v_pk_add_f32 v[6:7], v[10:11], v[4:5]
	v_pk_add_f32 v[8:9], v[12:13], v[2:3]
	ds_read_b128 v[10:13], v92
	s_waitcnt lgkmcnt(0)
	v_pk_add_f32 v[2:3], v[14:15], v[12:13]
	v_pk_add_f32 v[4:5], v[16:17], v[10:11]
	v_or_b32_e32 v12, s8, v83
	v_mov_b64_e32 v[10:11], s[60:61]
	v_mad_i64_i32 v[10:11], s[8:9], v0, s16, v[10:11]
	v_lshlrev_b32_e32 v0, 1, v12
	v_lshl_add_u64 v[14:15], v[10:11], 0, v[0:1]
	global_load_dwordx4 v[10:13], v[14:15], off
	v_exp_f32_e64 v0, -v8
	s_waitcnt vmcnt(0)
	v_lshlrev_b32_e32 v16, 16, v10
	v_add_f32_e32 v0, 1.0, v0
	v_rcp_f32_e32 v8, v0
	v_exp_f32_e64 v0, -v9
	v_and_b32_e32 v17, 0xffff0000, v10
	v_lshlrev_b32_e32 v10, 16, v11
	v_and_b32_e32 v11, 0xffff0000, v11
	v_add_f32_e32 v0, 1.0, v0
	v_rcp_f32_e32 v9, v0
	v_exp_f32_e64 v0, -v6
	v_pk_mul_f32 v[8:9], v[8:9], v[16:17]
	v_add_f32_e32 v0, 1.0, v0
	v_rcp_f32_e32 v6, v0
	v_exp_f32_e64 v0, -v7
	s_nop 0
	v_add_f32_e32 v0, 1.0, v0
	v_rcp_f32_e32 v7, v0
	v_exp_f32_e64 v0, -v4
	v_pk_mul_f32 v[6:7], v[6:7], v[10:11]
	v_add_f32_e32 v0, 1.0, v0
	v_rcp_f32_e32 v4, v0
	v_exp_f32_e64 v0, -v5
	v_lshlrev_b32_e32 v10, 16, v12
	v_and_b32_e32 v11, 0xffff0000, v12
	v_add_f32_e32 v0, 1.0, v0
	v_rcp_f32_e32 v5, v0
	v_exp_f32_e64 v0, -v2
	v_pk_mul_f32 v[4:5], v[4:5], v[10:11]
	v_add_f32_e32 v0, 1.0, v0
	v_rcp_f32_e32 v2, v0
	v_exp_f32_e64 v0, -v3
	v_lshlrev_b32_e32 v10, 16, v13
	v_and_b32_e32 v11, 0xffff0000, v13
	v_cvt_pk_bf16_f32 v4, v4, v5
	v_add_f32_e32 v0, 1.0, v0
	v_rcp_f32_e32 v3, v0
	s_nop 0
	v_pk_mul_f32 v[10:11], v[2:3], v[10:11]
	v_cvt_pk_bf16_f32 v2, v8, v9
	v_cvt_pk_bf16_f32 v3, v6, v7
	v_cvt_pk_bf16_f32 v5, v10, v11
	global_store_dwordx4 v[14:15], v[2:5], off
	s_barrier
	s_cbranch_scc1 .LBB0_1454

; #define MFMA32(a, b, c) __builtin_amdgcn_mfma_f32_32x32x16_bf16((a), (b), (c), 0, 0, 0)
; template <class Fin> __device__ __forceinline__ void ctx_gemm(const bf16_t* A, int lda, const bf16_t* Bt, int K, const Fin& fin, uchar* lds) {
;     ...
;     for (int id = blockIdx.x; id < 256; id += gridDim.x) {
;         const int tr = id >> 3, tc = id & 7;
;         const bf16_t* ap = A + (size_t)(tr * 32 + l32) * lda + wave * kw + 8 * hi;
;         const bf16_t* bp = Bt + (size_t)(tc * 128 + l32) * K + wave * kw + 8 * hi;
;         f32x16 acc0 = {}, acc1 = {}, acc2 = {}, acc3 = {};
; #pragma unroll 8
;         for (int s = 0; s < nst; ++s) {
;             const bf16x8 af = *(const bf16x8*)(ap + 16 * s);
;             const bf16x8 b0 = *(const bf16x8*)(bp + 16 * s), b1 = *(const bf16x8*)(bp + (size_t)32 * K + 16 * s), b2 = *(const bf16x8*)(bp + (size_t)64 * K + 16 * s), b3 = *(const bf16x8*)(bp + (size_t)96 * K + 16 * s);
;             acc0 = MFMA32(af, b0, acc0); acc1 = MFMA32(af, b1, acc1); acc2 = MFMA32(af, b2, acc2); acc3 = MFMA32(af, b3, acc3);
.LBB0_1457:
	s_and_b32 s7, s4, 0xffffffe0
	v_or_b32_e32 v0, s7, v70
	v_mad_i64_i32 v[104:105], s[8:9], v0, s16, v[66:67]
	s_and_b32 s8, s5, 0x380
	s_nop 0
	v_or_b32_e32 v0, s8, v70
	v_lshlrev_b32_e32 v0, 10, v0
	v_lshl_add_u64 v[106:107], v[68:69], 0, v[0:1]
	v_add_co_u32_e32 v108, vcc, 0x8000, v106
	global_load_dwordx4 v[50:53], v[104:105], off
	global_load_dwordx4 v[2:5], v[106:107], off
	v_addc_co_u32_e32 v109, vcc, 0, v107, vcc
	v_add_co_u32_e32 v110, vcc, 0x10000, v106
	s_waitcnt lgkmcnt(0)
	global_load_dwordx4 v[18:21], v[108:109], off
	v_addc_co_u32_e32 v111, vcc, 0, v107, vcc
	v_add_co_u32_e32 v112, vcc, 0x18000, v106
	global_load_dwordx4 v[34:37], v[110:111], off
	s_nop 0
	v_addc_co_u32_e32 v113, vcc, 0, v107, vcc
	global_load_dwordx4 v[54:57], v[112:113], off
	global_load_dwordx4 v[84:87], v[104:105], off offset:32
	global_load_dwordx4 v[88:91], v[106:107], off offset:32
	global_load_dwordx4 v[92:95], v[108:109], off offset:32
	global_load_dwordx4 v[96:99], v[110:111], off offset:32
	global_load_dwordx4 v[100:103], v[112:113], off offset:32
	v_add_u32_e32 v0, 0x400, v71
	s_add_i32 s6, s6, s90
	s_add_i32 s5, s5, s17
	s_add_i32 s4, s4, s64
	s_cmpk_lt_i32 s6, 0x100
	global_load_dwordx4 v[146:149], v[104:105], off offset:64
	global_load_dwordx4 v[150:153], v[106:107], off offset:64
	global_load_dwordx4 v[154:157], v[108:109], off offset:64
	global_load_dwordx4 v[158:161], v[110:111], off offset:64
	global_load_dwordx4 v[162:165], v[112:113], off offset:64
	global_load_dwordx4 v[166:169], v[104:105], off offset:96
	global_load_dwordx4 v[170:173], v[106:107], off offset:96
	global_load_dwordx4 v[174:177], v[108:109], off offset:96
	global_load_dwordx4 v[178:181], v[110:111], off offset:96
	global_load_dwordx4 v[182:185], v[112:113], off offset:96
	s_waitcnt vmcnt(10)
	v_mfma_f32_32x32x16_bf16 v[2:17], v[50:53], v[2:5], 0
	v_mfma_f32_32x32x16_bf16 v[18:33], v[50:53], v[18:21], 0
	v_mfma_f32_32x32x16_bf16 v[34:49], v[50:53], v[34:37], 0
	v_mfma_f32_32x32x16_bf16 v[50:65], v[50:53], v[54:57], 0
	v_mfma_f32_32x32x16_bf16 v[2:17], v[84:87], v[88:91], v[2:17]
	v_mfma_f32_32x32x16_bf16 v[18:33], v[84:87], v[92:95], v[18:33]
	v_mfma_f32_32x32x16_bf16 v[34:49], v[84:87], v[96:99], v[34:49]
	v_mfma_f32_32x32x16_bf16 v[50:65], v[84:87], v[100:103], v[50:65]
	s_waitcnt vmcnt(8)
	v_mfma_f32_32x32x16_bf16 v[2:17], v[146:149], v[150:153], v[2:17]
	s_waitcnt vmcnt(7)
	v_mfma_f32_32x32x16_bf16 v[18:33], v[146:149], v[154:157], v[18:33]
	s_waitcnt vmcnt(6)
	v_mfma_f32_32x32x16_bf16 v[34:49], v[146:149], v[158:161], v[34:49]
	s_waitcnt vmcnt(5)
	v_mfma_f32_32x32x16_bf16 v[50:65], v[146:149], v[162:165], v[50:65]
	s_waitcnt vmcnt(3)
	v_mfma_f32_32x32x16_bf16 v[2:17], v[166:169], v[170:173], v[2:17]
	s_waitcnt vmcnt(2)
	v_mfma_f32_32x32x16_bf16 v[18:33], v[166:169], v[174:177], v[18:33]
	s_waitcnt vmcnt(1)
	v_mfma_f32_32x32x16_bf16 v[34:49], v[166:169], v[178:181], v[34:49]
	s_waitcnt vmcnt(0)
	v_mfma_f32_32x32x16_bf16 v[50:65], v[166:169], v[182:185], v[50:65]
	s_nop 7
	ds_write2_b32 v71, v2, v18 offset1:32
	s_nop 2
	ds_write2_b32 v71, v34, v50 offset0:64 offset1:96
	ds_write2_b32 v71, v3, v19 offset0:128 offset1:160
	ds_write2_b32 v71, v35, v51 offset0:192 offset1:224
	ds_write2_b32 v0, v4, v20 offset1:32
	ds_write2_b32 v0, v36, v52 offset0:64 offset1:96
	ds_write2_b32 v0, v5, v21 offset0:128 offset1:160
	ds_write2_b32 v0, v37, v53 offset0:192 offset1:224
	v_add_u32_e32 v0, 0x1000, v71
	ds_write2_b32 v0, v6, v22 offset1:32
	ds_write2_b32 v0, v38, v54 offset0:64 offset1:96
	ds_write2_b32 v0, v7, v23 offset0:128 offset1:160
	ds_write2_b32 v0, v39, v55 offset0:192 offset1:224
	v_add_u32_e32 v0, 0x1400, v71
	ds_write2_b32 v0, v8, v24 offset1:32
	ds_write2_b32 v0, v40, v56 offset0:64 offset1:96
	ds_write2_b32 v0, v9, v25 offset0:128 offset1:160
	ds_write2_b32 v0, v41, v57 offset0:192 offset1:224
	v_add_u32_e32 v0, 0x2000, v71
	ds_write2_b32 v0, v10, v26 offset1:32
	ds_write2_b32 v0, v42, v58 offset0:64 offset1:96
	ds_write2_b32 v0, v11, v27 offset0:128 offset1:160
	ds_write2_b32 v0, v43, v59 offset0:192 offset1:224
	v_add_u32_e32 v0, 0x2400, v71
	ds_write2_b32 v0, v12, v28 offset1:32
	ds_write2_b32 v0, v44, v60 offset0:64 offset1:96
	ds_write2_b32 v0, v13, v29 offset0:128 offset1:160
	ds_write2_b32 v0, v45, v61 offset0:192 offset1:224
	v_add_u32_e32 v0, 0x3000, v71
	ds_write2_b32 v0, v14, v30 offset1:32
	ds_write2_b32 v0, v46, v62 offset0:64 offset1:96
	ds_write2_b32 v0, v15, v31 offset0:128 offset1:160
	ds_write2_b32 v0, v47, v63 offset0:192 offset1:224
	v_add_u32_e32 v0, 0x3400, v71
	ds_write2_b32 v0, v16, v32 offset1:32
	ds_write2_b32 v0, v48, v64 offset0:64 offset1:96
	ds_write2_b32 v0, v17, v33 offset0:128 offset1:160
	ds_write2_b32 v0, v49, v65 offset0:192 offset1:224
	s_waitcnt lgkmcnt(0)
	s_barrier
; __device__ __forceinline__ int crow(int r, int hi) { return (r & 3) + 8 * (r >> 2) + 4 * hi; }
; template <class Fin> __device__ __forceinline__ void ctx_gemm(const bf16_t* A, int lda, const bf16_t* Bt, int K, const Fin& fin, uchar* lds) {
;     ...
;         float* rw = red + wave * 4096 + l32;
; #pragma unroll
;         for (int r = 0; r < 16; ++r) { float* q = rw + crow(r, hi) * 128; q[0] = acc0[r]; q[32] = acc1[r]; q[64] = acc2[r]; q[96] = acc3[r]; }
;         __syncthreads();
;         const int row = tid >> 4, c8 = (tid & 15) * 8;
;         f32x4 s0 = {}, s1 = {};
; #pragma unroll
;         for (int w = 0; w < 8; ++w) { s0 += *(const f32x4*)(red + w * 4096 + row * 128 + c8); s1 += *(const f32x4*)(red + w * 4096 + row * 128 + c8 + 4); }
;         fin(tr * 32 + row, tc * 128 + c8, s0, s1);
	ds_read_b128 v[2:5], v74
	ds_read_b128 v[6:9], v74 offset:16
	v_or_b32_e32 v0, s8, v73
	v_lshlrev_b32_e32 v0, 1, v0
	s_waitcnt lgkmcnt(1)
	v_pk_add_f32 v[10:11], v[4:5], 0 op_sel_hi:[1,0]
	v_pk_add_f32 v[12:13], v[2:3], 0 op_sel_hi:[1,0]
	ds_read_b128 v[2:5], v74 offset:16384
	s_waitcnt lgkmcnt(1)
	v_pk_add_f32 v[8:9], v[8:9], 0 op_sel_hi:[1,0]
	v_pk_add_f32 v[6:7], v[6:7], 0 op_sel_hi:[1,0]
	s_waitcnt lgkmcnt(0)
	v_pk_add_f32 v[10:11], v[10:11], v[4:5]
	v_pk_add_f32 v[12:13], v[12:13], v[2:3]
	ds_read_b128 v[2:5], v74 offset:16400
	s_waitcnt lgkmcnt(0)
	v_pk_add_f32 v[8:9], v[8:9], v[4:5]
	v_pk_add_f32 v[6:7], v[6:7], v[2:3]
	ds_read_b128 v[2:5], v74 offset:32768
	s_waitcnt lgkmcnt(0)
	v_pk_add_f32 v[10:11], v[10:11], v[4:5]
	v_pk_add_f32 v[12:13], v[12:13], v[2:3]
	ds_read_b128 v[2:5], v74 offset:32784
	s_waitcnt lgkmcnt(0)
	v_pk_add_f32 v[8:9], v[8:9], v[4:5]
	v_pk_add_f32 v[6:7], v[6:7], v[2:3]
	ds_read_b128 v[2:5], v74 offset:49152
	s_waitcnt lgkmcnt(0)
	v_pk_add_f32 v[10:11], v[10:11], v[4:5]
	v_pk_add_f32 v[12:13], v[12:13], v[2:3]
	ds_read_b128 v[2:5], v74 offset:49168
	s_waitcnt lgkmcnt(0)
	v_pk_add_f32 v[8:9], v[8:9], v[4:5]
	v_pk_add_f32 v[6:7], v[6:7], v[2:3]
	ds_read_b128 v[2:5], v75
	s_waitcnt lgkmcnt(0)
	v_pk_add_f32 v[10:11], v[10:11], v[4:5]
	v_pk_add_f32 v[12:13], v[12:13], v[2:3]
	ds_read_b128 v[2:5], v76
	s_waitcnt lgkmcnt(0)
	v_pk_add_f32 v[8:9], v[8:9], v[4:5]
	v_pk_add_f32 v[6:7], v[6:7], v[2:3]
	ds_read_b128 v[2:5], v77
	s_waitcnt lgkmcnt(0)
	v_pk_add_f32 v[10:11], v[10:11], v[4:5]
	v_pk_add_f32 v[12:13], v[12:13], v[2:3]
	ds_read_b128 v[2:5], v78
	s_waitcnt lgkmcnt(0)
	v_pk_add_f32 v[8:9], v[8:9], v[4:5]
	v_pk_add_f32 v[6:7], v[6:7], v[2:3]
	ds_read_b128 v[2:5], v79
	s_waitcnt lgkmcnt(0)
	v_pk_add_f32 v[10:11], v[10:11], v[4:5]
	v_pk_add_f32 v[12:13], v[12:13], v[2:3]
	ds_read_b128 v[2:5], v80
	s_waitcnt lgkmcnt(0)
	v_pk_add_f32 v[8:9], v[8:9], v[4:5]
	v_pk_add_f32 v[6:7], v[6:7], v[2:3]
	ds_read_b128 v[2:5], v81
	s_waitcnt lgkmcnt(0)
	v_pk_add_f32 v[10:11], v[10:11], v[4:5]
	v_pk_add_f32 v[12:13], v[12:13], v[2:3]
	ds_read_b128 v[2:5], v82
	s_waitcnt lgkmcnt(0)
	v_pk_add_f32 v[8:9], v[8:9], v[4:5]
	v_pk_add_f32 v[4:5], v[6:7], v[2:3]
	v_add_u32_e32 v2, s7, v72
	v_ashrrev_i32_e32 v3, 31, v2
	v_lshlrev_b64 v[2:3], 11, v[2:3]
	v_lshl_add_u64 v[2:3], s[18:19], 0, v[2:3]
	v_lshl_add_u64 v[6:7], v[2:3], 0, v[0:1]
	v_cvt_pk_bf16_f32 v2, v12, v13
	v_cvt_pk_bf16_f32 v3, v10, v11
	v_cvt_pk_bf16_f32 v4, v4, v5
	v_cvt_pk_bf16_f32 v5, v8, v9
	global_store_dwordx4 v[6:7], v[2:5], off
	s_barrier
	s_cbranch_scc1 .LBB0_1457

; #define MFMA32(a, b, c) __builtin_amdgcn_mfma_f32_32x32x16_bf16((a), (b), (c), 0, 0, 0)
; template <class Fin> __device__ __forceinline__ void ctx_gemm(const bf16_t* A, int lda, const bf16_t* Bt, int K, const Fin& fin, uchar* lds) {
;     ...
;     for (int id = blockIdx.x; id < 256; id += gridDim.x) {
;         const int tr = id >> 3, tc = id & 7;
;         const bf16_t* ap = A + (size_t)(tr * 32 + l32) * lda + wave * kw + 8 * hi;
;         const bf16_t* bp = Bt + (size_t)(tc * 128 + l32) * K + wave * kw + 8 * hi;
;         f32x16 acc0 = {}, acc1 = {}, acc2 = {}, acc3 = {};
; #pragma unroll 8
;         for (int s = 0; s < nst; ++s) {
;             const bf16x8 af = *(const bf16x8*)(ap + 16 * s);
;             const bf16x8 b0 = *(const bf16x8*)(bp + 16 * s), b1 = *(const bf16x8*)(bp + (size_t)32 * K + 16 * s), b2 = *(const bf16x8*)(bp + (size_t)64 * K + 16 * s), b3 = *(const bf16x8*)(bp + (size_t)96 * K + 16 * s);
;             acc0 = MFMA32(af, b0, acc0); acc1 = MFMA32(af, b1, acc1); acc2 = MFMA32(af, b2, acc2); acc3 = MFMA32(af, b3, acc3);
.LBB0_1460:
	s_and_b32 s8, s5, 0x380
	v_or_b32_e32 v0, s8, v80
	v_lshlrev_b32_e32 v0, 11, v0
	v_lshl_add_u64 v[78:79], v[68:69], 0, v[0:1]
	v_add_co_u32_e32 v76, vcc, s33, v78
	s_and_b32 s7, s4, 0xffffffe0
	s_nop 0
	v_addc_co_u32_e32 v77, vcc, 0, v79, vcc
	v_or_b32_e32 v2, s7, v80
	v_add_co_u32_e32 v74, vcc, s13, v78
	v_ashrrev_i32_e32 v3, 31, v2
	s_nop 0
	v_addc_co_u32_e32 v75, vcc, 0, v79, vcc
	v_lshlrev_b64 v[2:3], 11, v[2:3]
	v_add_co_u32_e32 v72, vcc, s22, v78
	v_lshl_add_u64 v[70:71], v[66:67], 0, v[2:3]
	s_nop 0
	v_addc_co_u32_e32 v73, vcc, 0, v79, vcc
	global_load_dwordx4 v[50:53], v[70:71], off
	global_load_dwordx4 v[2:5], v[78:79], off
	s_waitcnt lgkmcnt(0)
	global_load_dwordx4 v[18:21], v[76:77], off
	global_load_dwordx4 v[34:37], v[74:75], off
	global_load_dwordx4 v[54:57], v[72:73], off
	global_load_dwordx4 v[94:97], v[70:71], off offset:32
	global_load_dwordx4 v[98:101], v[78:79], off offset:32
	global_load_dwordx4 v[102:105], v[76:77], off offset:32
	global_load_dwordx4 v[106:109], v[74:75], off offset:32
	global_load_dwordx4 v[110:113], v[72:73], off offset:32
	v_add_u32_e32 v0, 0x400, v81
	s_add_i32 s6, s6, s90
	s_add_i32 s5, s5, s17
	s_add_i32 s4, s4, s64
	s_cmpk_lt_i32 s6, 0x100
	global_load_dwordx4 v[146:149], v[70:71], off offset:64
	global_load_dwordx4 v[150:153], v[78:79], off offset:64
	global_load_dwordx4 v[154:157], v[76:77], off offset:64
	global_load_dwordx4 v[158:161], v[74:75], off offset:64
	global_load_dwordx4 v[162:165], v[72:73], off offset:64
	global_load_dwordx4 v[166:169], v[70:71], off offset:96
	global_load_dwordx4 v[170:173], v[78:79], off offset:96
	global_load_dwordx4 v[174:177], v[76:77], off offset:96
	global_load_dwordx4 v[178:181], v[74:75], off offset:96
	global_load_dwordx4 v[182:185], v[72:73], off offset:96
	global_load_dwordx4 v[194:197], v[70:71], off offset:128
	global_load_dwordx4 v[198:201], v[78:79], off offset:128
	global_load_dwordx4 v[202:205], v[76:77], off offset:128
	global_load_dwordx4 v[220:223], v[74:75], off offset:128
	global_load_dwordx4 v[224:227], v[72:73], off offset:128
	s_waitcnt vmcnt(15)
	v_mfma_f32_32x32x16_bf16 v[2:17], v[50:53], v[2:5], 0
	v_mfma_f32_32x32x16_bf16 v[18:33], v[50:53], v[18:21], 0
	v_mfma_f32_32x32x16_bf16 v[34:49], v[50:53], v[34:37], 0
	v_mfma_f32_32x32x16_bf16 v[50:65], v[50:53], v[54:57], 0
	v_mfma_f32_32x32x16_bf16 v[2:17], v[94:97], v[98:101], v[2:17]
	v_mfma_f32_32x32x16_bf16 v[18:33], v[94:97], v[102:105], v[18:33]
	v_mfma_f32_32x32x16_bf16 v[34:49], v[94:97], v[106:109], v[34:49]
	v_mfma_f32_32x32x16_bf16 v[50:65], v[94:97], v[110:113], v[50:65]
	global_load_dwordx4 v[94:97], v[70:71], off offset:160
	global_load_dwordx4 v[98:101], v[78:79], off offset:160
	global_load_dwordx4 v[102:105], v[76:77], off offset:160
	global_load_dwordx4 v[106:109], v[74:75], off offset:160
	global_load_dwordx4 v[110:113], v[72:73], off offset:160
	s_waitcnt vmcnt(18)
	v_mfma_f32_32x32x16_bf16 v[2:17], v[146:149], v[150:153], v[2:17]
	s_waitcnt vmcnt(17)
	v_mfma_f32_32x32x16_bf16 v[18:33], v[146:149], v[154:157], v[18:33]
	s_waitcnt vmcnt(16)
	v_mfma_f32_32x32x16_bf16 v[34:49], v[146:149], v[158:161], v[34:49]
	s_waitcnt vmcnt(15)
	v_mfma_f32_32x32x16_bf16 v[50:65], v[146:149], v[162:165], v[50:65]
	global_load_dwordx4 v[146:149], v[70:71], off offset:192
	global_load_dwordx4 v[150:153], v[78:79], off offset:192
	global_load_dwordx4 v[154:157], v[76:77], off offset:192
	global_load_dwordx4 v[158:161], v[74:75], off offset:192
	global_load_dwordx4 v[162:165], v[72:73], off offset:192
	s_waitcnt vmcnt(18)
	v_mfma_f32_32x32x16_bf16 v[2:17], v[166:169], v[170:173], v[2:17]
	s_waitcnt vmcnt(17)
	v_mfma_f32_32x32x16_bf16 v[18:33], v[166:169], v[174:177], v[18:33]
	s_waitcnt vmcnt(16)
	v_mfma_f32_32x32x16_bf16 v[34:49], v[166:169], v[178:181], v[34:49]
	s_waitcnt vmcnt(15)
	v_mfma_f32_32x32x16_bf16 v[50:65], v[166:169], v[182:185], v[50:65]
	global_load_dwordx4 v[166:169], v[70:71], off offset:224
	global_load_dwordx4 v[170:173], v[78:79], off offset:224
	global_load_dwordx4 v[174:177], v[76:77], off offset:224
	global_load_dwordx4 v[178:181], v[74:75], off offset:224
	global_load_dwordx4 v[182:185], v[72:73], off offset:224
	s_waitcnt vmcnt(18)
	v_mfma_f32_32x32x16_bf16 v[2:17], v[194:197], v[198:201], v[2:17]
	s_waitcnt vmcnt(17)
	v_mfma_f32_32x32x16_bf16 v[18:33], v[194:197], v[202:205], v[18:33]
	s_waitcnt vmcnt(16)
	v_mfma_f32_32x32x16_bf16 v[34:49], v[194:197], v[220:223], v[34:49]
	s_waitcnt vmcnt(15)
	v_mfma_f32_32x32x16_bf16 v[50:65], v[194:197], v[224:227], v[50:65]
	s_waitcnt vmcnt(13)
	v_mfma_f32_32x32x16_bf16 v[2:17], v[94:97], v[98:101], v[2:17]
	s_waitcnt vmcnt(12)
	v_mfma_f32_32x32x16_bf16 v[18:33], v[94:97], v[102:105], v[18:33]
	s_waitcnt vmcnt(11)
	v_mfma_f32_32x32x16_bf16 v[34:49], v[94:97], v[106:109], v[34:49]
	s_waitcnt vmcnt(10)
	v_mfma_f32_32x32x16_bf16 v[50:65], v[94:97], v[110:113], v[50:65]
	s_waitcnt vmcnt(8)
	v_mfma_f32_32x32x16_bf16 v[2:17], v[146:149], v[150:153], v[2:17]
	s_waitcnt vmcnt(7)
	v_mfma_f32_32x32x16_bf16 v[18:33], v[146:149], v[154:157], v[18:33]
	s_waitcnt vmcnt(6)
	v_mfma_f32_32x32x16_bf16 v[34:49], v[146:149], v[158:161], v[34:49]
	s_waitcnt vmcnt(5)
	v_mfma_f32_32x32x16_bf16 v[50:65], v[146:149], v[162:165], v[50:65]
	s_waitcnt vmcnt(3)
	v_mfma_f32_32x32x16_bf16 v[2:17], v[166:169], v[170:173], v[2:17]
	s_waitcnt vmcnt(2)
	v_mfma_f32_32x32x16_bf16 v[18:33], v[166:169], v[174:177], v[18:33]
	s_waitcnt vmcnt(1)
	v_mfma_f32_32x32x16_bf16 v[34:49], v[166:169], v[178:181], v[34:49]
	s_waitcnt vmcnt(0)
; __device__ __forceinline__ int crow(int r, int hi) { return (r & 3) + 8 * (r >> 2) + 4 * hi; }
; #define MFMA32(a, b, c) __builtin_amdgcn_mfma_f32_32x32x16_bf16((a), (b), (c), 0, 0, 0)
; template <class Fin> __device__ __forceinline__ void ctx_gemm(const bf16_t* A, int lda, const bf16_t* Bt, int K, const Fin& fin, uchar* lds) {
;     ...
;             acc0 = MFMA32(af, b0, acc0); acc1 = MFMA32(af, b1, acc1); acc2 = MFMA32(af, b2, acc2); acc3 = MFMA32(af, b3, acc3);
;         }
;         float* rw = red + wave * 4096 + l32;
; #pragma unroll
;         for (int r = 0; r < 16; ++r) { float* q = rw + crow(r, hi) * 128; q[0] = acc0[r]; q[32] = acc1[r]; q[64] = acc2[r]; q[96] = acc3[r]; }
;         __syncthreads();
;         const int row = tid >> 4, c8 = (tid & 15) * 8;
;         f32x4 s0 = {}, s1 = {};
; #pragma unroll
;         for (int w = 0; w < 8; ++w) { s0 += *(const f32x4*)(red + w * 4096 + row * 128 + c8); s1 += *(const f32x4*)(red + w * 4096 + row * 128 + c8 + 4); }
;         fin(tr * 32 + row, tc * 128 + c8, s0, s1);
	v_mfma_f32_32x32x16_bf16 v[50:65], v[166:169], v[182:185], v[50:65]
	s_nop 7
	ds_write2_b32 v81, v2, v18 offset1:32
	s_nop 2
	ds_write2_b32 v81, v34, v50 offset0:64 offset1:96
	ds_write2_b32 v81, v3, v19 offset0:128 offset1:160
	ds_write2_b32 v81, v35, v51 offset0:192 offset1:224
	ds_write2_b32 v0, v4, v20 offset1:32
	ds_write2_b32 v0, v36, v52 offset0:64 offset1:96
	ds_write2_b32 v0, v5, v21 offset0:128 offset1:160
	ds_write2_b32 v0, v37, v53 offset0:192 offset1:224
	v_add_u32_e32 v0, 0x1000, v81
	ds_write2_b32 v0, v6, v22 offset1:32
	ds_write2_b32 v0, v38, v54 offset0:64 offset1:96
	ds_write2_b32 v0, v7, v23 offset0:128 offset1:160
	ds_write2_b32 v0, v39, v55 offset0:192 offset1:224
	v_add_u32_e32 v0, 0x1400, v81
	ds_write2_b32 v0, v8, v24 offset1:32
	ds_write2_b32 v0, v40, v56 offset0:64 offset1:96
	ds_write2_b32 v0, v9, v25 offset0:128 offset1:160
	ds_write2_b32 v0, v41, v57 offset0:192 offset1:224
	v_add_u32_e32 v0, 0x2000, v81
	ds_write2_b32 v0, v10, v26 offset1:32
	ds_write2_b32 v0, v42, v58 offset0:64 offset1:96
	ds_write2_b32 v0, v11, v27 offset0:128 offset1:160
	ds_write2_b32 v0, v43, v59 offset0:192 offset1:224
	v_add_u32_e32 v0, 0x2400, v81
	ds_write2_b32 v0, v12, v28 offset1:32
	ds_write2_b32 v0, v44, v60 offset0:64 offset1:96
	ds_write2_b32 v0, v13, v29 offset0:128 offset1:160
	ds_write2_b32 v0, v45, v61 offset0:192 offset1:224
	v_add_u32_e32 v0, 0x3000, v81
	ds_write2_b32 v0, v14, v30 offset1:32
	ds_write2_b32 v0, v46, v62 offset0:64 offset1:96
	ds_write2_b32 v0, v15, v31 offset0:128 offset1:160
	ds_write2_b32 v0, v47, v63 offset0:192 offset1:224
	v_add_u32_e32 v0, 0x3400, v81
	ds_write2_b32 v0, v16, v32 offset1:32
	ds_write2_b32 v0, v48, v64 offset0:64 offset1:96
	ds_write2_b32 v0, v17, v33 offset0:128 offset1:160
	ds_write2_b32 v0, v49, v65 offset0:192 offset1:224
	s_waitcnt lgkmcnt(0)
	s_barrier
	ds_read_b128 v[2:5], v84
	ds_read_b128 v[6:9], v84 offset:16
	v_or_b32_e32 v0, s8, v83
	v_lshlrev_b32_e32 v0, 1, v0
	s_waitcnt lgkmcnt(1)
	v_pk_add_f32 v[10:11], v[4:5], 0 op_sel_hi:[1,0]
	v_pk_add_f32 v[12:13], v[2:3], 0 op_sel_hi:[1,0]
	ds_read_b128 v[2:5], v84 offset:16384
	s_waitcnt lgkmcnt(1)
	v_pk_add_f32 v[8:9], v[8:9], 0 op_sel_hi:[1,0]
	v_pk_add_f32 v[6:7], v[6:7], 0 op_sel_hi:[1,0]
	s_waitcnt lgkmcnt(0)
	v_pk_add_f32 v[10:11], v[10:11], v[4:5]
	v_pk_add_f32 v[12:13], v[12:13], v[2:3]
	ds_read_b128 v[2:5], v84 offset:16400
	s_waitcnt lgkmcnt(0)
	v_pk_add_f32 v[8:9], v[8:9], v[4:5]
	v_pk_add_f32 v[6:7], v[6:7], v[2:3]
	ds_read_b128 v[2:5], v84 offset:32768
	s_waitcnt lgkmcnt(0)
	v_pk_add_f32 v[10:11], v[10:11], v[4:5]
	v_pk_add_f32 v[12:13], v[12:13], v[2:3]
	ds_read_b128 v[2:5], v84 offset:32784
	s_waitcnt lgkmcnt(0)
	v_pk_add_f32 v[8:9], v[8:9], v[4:5]
	v_pk_add_f32 v[6:7], v[6:7], v[2:3]
	ds_read_b128 v[2:5], v84 offset:49152
	s_waitcnt lgkmcnt(0)
	v_pk_add_f32 v[10:11], v[10:11], v[4:5]
	v_pk_add_f32 v[12:13], v[12:13], v[2:3]
	ds_read_b128 v[2:5], v84 offset:49168
	s_waitcnt lgkmcnt(0)
	v_pk_add_f32 v[8:9], v[8:9], v[4:5]
	v_pk_add_f32 v[6:7], v[6:7], v[2:3]
	ds_read_b128 v[2:5], v85
	s_waitcnt lgkmcnt(0)
	v_pk_add_f32 v[10:11], v[10:11], v[4:5]
	v_pk_add_f32 v[12:13], v[12:13], v[2:3]
	ds_read_b128 v[2:5], v86
	s_waitcnt lgkmcnt(0)
	v_pk_add_f32 v[8:9], v[8:9], v[4:5]
	v_pk_add_f32 v[6:7], v[6:7], v[2:3]
	ds_read_b128 v[2:5], v87
	s_waitcnt lgkmcnt(0)
	v_pk_add_f32 v[10:11], v[10:11], v[4:5]
	v_pk_add_f32 v[12:13], v[12:13], v[2:3]
	ds_read_b128 v[2:5], v88
	s_waitcnt lgkmcnt(0)
	v_pk_add_f32 v[8:9], v[8:9], v[4:5]
	v_pk_add_f32 v[6:7], v[6:7], v[2:3]
	ds_read_b128 v[2:5], v89
	s_waitcnt lgkmcnt(0)
	v_pk_add_f32 v[10:11], v[10:11], v[4:5]
	v_pk_add_f32 v[12:13], v[12:13], v[2:3]
	ds_read_b128 v[2:5], v90
	s_waitcnt lgkmcnt(0)
	v_pk_add_f32 v[14:15], v[8:9], v[4:5]
	v_pk_add_f32 v[16:17], v[6:7], v[2:3]
	ds_read_b128 v[2:5], v91
	s_waitcnt lgkmcnt(0)
	v_pk_add_f32 v[6:7], v[10:11], v[4:5]
	v_pk_add_f32 v[8:9], v[12:13], v[2:3]
	ds_read_b128 v[10:13], v92
	s_waitcnt lgkmcnt(0)
	v_pk_add_f32 v[4:5], v[16:17], v[10:11]
	v_add_u32_e32 v10, s7, v82
	v_pk_add_f32 v[2:3], v[14:15], v[12:13]
	v_ashrrev_i32_e32 v11, 31, v10
	v_mov_b64_e32 v[12:13], s[60:61]
	v_mad_i64_i32 v[12:13], s[8:9], v10, s16, v[12:13]
	v_lshlrev_b64 v[10:11], 11, v[10:11]
	v_lshl_add_u64 v[10:11], s[18:19], 0, v[10:11]
	v_lshl_add_u64 v[20:21], v[12:13], 0, v[0:1]
	v_lshl_add_u64 v[10:11], v[10:11], 0, v[0:1]
	global_load_dwordx4 v[12:15], v[20:21], off
	global_load_dwordx4 v[16:19], v[10:11], off
	v_exp_f32_e64 v0, -v8
	s_waitcnt vmcnt(1)
	v_lshlrev_b32_e32 v10, 16, v12
	v_add_f32_e32 v0, 1.0, v0
	v_rcp_f32_e32 v8, v0
	v_exp_f32_e64 v0, -v9
	v_and_b32_e32 v11, 0xffff0000, v12
	s_waitcnt vmcnt(0)
	v_lshlrev_b32_e32 v22, 16, v16
	v_and_b32_e32 v23, 0xffff0000, v16
	v_add_f32_e32 v0, 1.0, v0
	v_rcp_f32_e32 v9, v0
	v_exp_f32_e64 v0, -v6
	v_lshlrev_b32_e32 v12, 16, v17
	v_pk_fma_f32 v[8:9], v[8:9], v[22:23], v[10:11]
	v_add_f32_e32 v0, 1.0, v0
	v_rcp_f32_e32 v6, v0
	v_exp_f32_e64 v0, -v7
	v_lshlrev_b32_e32 v10, 16, v13
	v_and_b32_e32 v11, 0xffff0000, v13
	v_and_b32_e32 v13, 0xffff0000, v17
	v_add_f32_e32 v0, 1.0, v0
	v_rcp_f32_e32 v7, v0
	v_exp_f32_e64 v0, -v4
	v_pk_fma_f32 v[6:7], v[6:7], v[12:13], v[10:11]
	v_add_f32_e32 v0, 1.0, v0
	v_rcp_f32_e32 v4, v0
	v_exp_f32_e64 v0, -v5
	v_lshlrev_b32_e32 v10, 16, v14
	v_and_b32_e32 v11, 0xffff0000, v14
	v_lshlrev_b32_e32 v12, 16, v18
	v_add_f32_e32 v0, 1.0, v0
	v_rcp_f32_e32 v5, v0
	v_exp_f32_e64 v0, -v2
	v_and_b32_e32 v13, 0xffff0000, v18
	v_pk_fma_f32 v[4:5], v[4:5], v[12:13], v[10:11]
	v_add_f32_e32 v0, 1.0, v0
	v_rcp_f32_e32 v2, v0
	v_exp_f32_e64 v0, -v3
	v_lshlrev_b32_e32 v10, 16, v15
	v_and_b32_e32 v11, 0xffff0000, v15
	v_lshlrev_b32_e32 v12, 16, v19
	v_add_f32_e32 v0, 1.0, v0
	v_rcp_f32_e32 v3, v0
	v_and_b32_e32 v13, 0xffff0000, v19
	v_cvt_pk_bf16_f32 v4, v4, v5
	v_pk_fma_f32 v[10:11], v[2:3], v[12:13], v[10:11]
	v_cvt_pk_bf16_f32 v2, v8, v9
	v_cvt_pk_bf16_f32 v3, v6, v7
	v_cvt_pk_bf16_f32 v5, v10, v11
	global_store_dwordx4 v[20:21], v[2:5], off
	s_barrier
	s_cbranch_scc1 .LBB0_1460

; #define MFMA32(a, b, c) __builtin_amdgcn_mfma_f32_32x32x16_bf16((a), (b), (c), 0, 0, 0)
; template <class Fin> __device__ __forceinline__ void ctx_gemm(const bf16_t* A, int lda, const bf16_t* Bt, int K, const Fin& fin, uchar* lds) {
;     ...
;     for (int id = blockIdx.x; id < 256; id += gridDim.x) {
;         const int tr = id >> 3, tc = id & 7;
;         const bf16_t* ap = A + (size_t)(tr * 32 + l32) * lda + wave * kw + 8 * hi;
;         const bf16_t* bp = Bt + (size_t)(tc * 128 + l32) * K + wave * kw + 8 * hi;
;         f32x16 acc0 = {}, acc1 = {}, acc2 = {}, acc3 = {};
; #pragma unroll 8
;         for (int s = 0; s < nst; ++s) {
;             const bf16x8 af = *(const bf16x8*)(ap + 16 * s);
;             const bf16x8 b0 = *(const bf16x8*)(bp + 16 * s), b1 = *(const bf16x8*)(bp + (size_t)32 * K + 16 * s), b2 = *(const bf16x8*)(bp + (size_t)64 * K + 16 * s), b3 = *(const bf16x8*)(bp + (size_t)96 * K + 16 * s);
;             acc0 = MFMA32(af, b0, acc0); acc1 = MFMA32(af, b1, acc1); acc2 = MFMA32(af, b2, acc2); acc3 = MFMA32(af, b3, acc3);
.LBB0_1539:
	s_and_b32 s7, s4, 0xffffffe0
	v_or_b32_e32 v0, s7, v80
	v_mad_i64_i32 v[78:79], s[8:9], v0, s16, v[66:67]
	s_and_b32 s8, s5, 0x380
	s_nop 0
	v_or_b32_e32 v0, s8, v80
	v_lshlrev_b32_e32 v0, 11, v0
	v_lshl_add_u64 v[76:77], v[68:69], 0, v[0:1]
	v_add_co_u32_e32 v74, vcc, 0x10000, v76
	global_load_dwordx4 v[50:53], v[78:79], off
	global_load_dwordx4 v[2:5], v[76:77], off
	v_addc_co_u32_e32 v75, vcc, 0, v77, vcc
	v_add_co_u32_e32 v72, vcc, 0x20000, v76
	s_waitcnt lgkmcnt(0)
	global_load_dwordx4 v[18:21], v[74:75], off
	v_addc_co_u32_e32 v73, vcc, 0, v77, vcc
	v_add_co_u32_e32 v70, vcc, 0x30000, v76
	global_load_dwordx4 v[34:37], v[72:73], off
	s_nop 0
	v_addc_co_u32_e32 v71, vcc, 0, v77, vcc
	global_load_dwordx4 v[54:57], v[70:71], off
	global_load_dwordx4 v[94:97], v[78:79], off offset:32
	global_load_dwordx4 v[98:101], v[76:77], off offset:32
	global_load_dwordx4 v[102:105], v[74:75], off offset:32
	global_load_dwordx4 v[106:109], v[72:73], off offset:32
	global_load_dwordx4 v[110:113], v[70:71], off offset:32
	v_add_u32_e32 v0, 0x400, v81
	s_add_i32 s6, s6, s90
	s_add_i32 s5, s5, s17
	s_add_i32 s4, s4, s64
	s_cmpk_lt_i32 s6, 0x100
	global_load_dwordx4 v[146:149], v[78:79], off offset:64
	global_load_dwordx4 v[150:153], v[76:77], off offset:64
	global_load_dwordx4 v[154:157], v[74:75], off offset:64
	global_load_dwordx4 v[158:161], v[72:73], off offset:64
	global_load_dwordx4 v[162:165], v[70:71], off offset:64
	global_load_dwordx4 v[166:169], v[78:79], off offset:96
	global_load_dwordx4 v[170:173], v[76:77], off offset:96
	global_load_dwordx4 v[174:177], v[74:75], off offset:96
	global_load_dwordx4 v[178:181], v[72:73], off offset:96
	global_load_dwordx4 v[182:185], v[70:71], off offset:96
	global_load_dwordx4 v[194:197], v[78:79], off offset:128
	global_load_dwordx4 v[198:201], v[76:77], off offset:128
	global_load_dwordx4 v[202:205], v[74:75], off offset:128
	global_load_dwordx4 v[220:223], v[72:73], off offset:128
	global_load_dwordx4 v[224:227], v[70:71], off offset:128
	s_waitcnt vmcnt(15)
	v_mfma_f32_32x32x16_bf16 v[2:17], v[50:53], v[2:5], 0
	v_mfma_f32_32x32x16_bf16 v[18:33], v[50:53], v[18:21], 0
	v_mfma_f32_32x32x16_bf16 v[34:49], v[50:53], v[34:37], 0
	v_mfma_f32_32x32x16_bf16 v[50:65], v[50:53], v[54:57], 0
	v_mfma_f32_32x32x16_bf16 v[2:17], v[94:97], v[98:101], v[2:17]
	v_mfma_f32_32x32x16_bf16 v[18:33], v[94:97], v[102:105], v[18:33]
	v_mfma_f32_32x32x16_bf16 v[34:49], v[94:97], v[106:109], v[34:49]
	v_mfma_f32_32x32x16_bf16 v[50:65], v[94:97], v[110:113], v[50:65]
	global_load_dwordx4 v[94:97], v[78:79], off offset:160
	global_load_dwordx4 v[98:101], v[76:77], off offset:160
	global_load_dwordx4 v[102:105], v[74:75], off offset:160
	global_load_dwordx4 v[106:109], v[72:73], off offset:160
	global_load_dwordx4 v[110:113], v[70:71], off offset:160
	s_waitcnt vmcnt(18)
	v_mfma_f32_32x32x16_bf16 v[2:17], v[146:149], v[150:153], v[2:17]
	s_waitcnt vmcnt(17)
	v_mfma_f32_32x32x16_bf16 v[18:33], v[146:149], v[154:157], v[18:33]
	s_waitcnt vmcnt(16)
	v_mfma_f32_32x32x16_bf16 v[34:49], v[146:149], v[158:161], v[34:49]
	s_waitcnt vmcnt(15)
	v_mfma_f32_32x32x16_bf16 v[50:65], v[146:149], v[162:165], v[50:65]
	global_load_dwordx4 v[146:149], v[78:79], off offset:192
	global_load_dwordx4 v[150:153], v[76:77], off offset:192
	global_load_dwordx4 v[154:157], v[74:75], off offset:192
	global_load_dwordx4 v[158:161], v[72:73], off offset:192
	global_load_dwordx4 v[162:165], v[70:71], off offset:192
	s_waitcnt vmcnt(18)
	v_mfma_f32_32x32x16_bf16 v[2:17], v[166:169], v[170:173], v[2:17]
	s_waitcnt vmcnt(17)
	v_mfma_f32_32x32x16_bf16 v[18:33], v[166:169], v[174:177], v[18:33]
	s_waitcnt vmcnt(16)
	v_mfma_f32_32x32x16_bf16 v[34:49], v[166:169], v[178:181], v[34:49]
	s_waitcnt vmcnt(15)
	v_mfma_f32_32x32x16_bf16 v[50:65], v[166:169], v[182:185], v[50:65]
	global_load_dwordx4 v[166:169], v[78:79], off offset:224
	global_load_dwordx4 v[170:173], v[76:77], off offset:224
	global_load_dwordx4 v[174:177], v[74:75], off offset:224
	global_load_dwordx4 v[178:181], v[72:73], off offset:224
	global_load_dwordx4 v[182:185], v[70:71], off offset:224
	s_waitcnt vmcnt(18)
	v_mfma_f32_32x32x16_bf16 v[2:17], v[194:197], v[198:201], v[2:17]
	s_waitcnt vmcnt(17)
	v_mfma_f32_32x32x16_bf16 v[18:33], v[194:197], v[202:205], v[18:33]
	s_waitcnt vmcnt(16)
	v_mfma_f32_32x32x16_bf16 v[34:49], v[194:197], v[220:223], v[34:49]
	s_waitcnt vmcnt(15)
	v_mfma_f32_32x32x16_bf16 v[50:65], v[194:197], v[224:227], v[50:65]
	s_waitcnt vmcnt(13)
	v_mfma_f32_32x32x16_bf16 v[2:17], v[94:97], v[98:101], v[2:17]
	s_waitcnt vmcnt(12)
	v_mfma_f32_32x32x16_bf16 v[18:33], v[94:97], v[102:105], v[18:33]
	s_waitcnt vmcnt(11)
	v_mfma_f32_32x32x16_bf16 v[34:49], v[94:97], v[106:109], v[34:49]
	s_waitcnt vmcnt(10)
	v_mfma_f32_32x32x16_bf16 v[50:65], v[94:97], v[110:113], v[50:65]
	s_waitcnt vmcnt(8)
	v_mfma_f32_32x32x16_bf16 v[2:17], v[146:149], v[150:153], v[2:17]
	s_waitcnt vmcnt(7)
	v_mfma_f32_32x32x16_bf16 v[18:33], v[146:149], v[154:157], v[18:33]
	s_waitcnt vmcnt(6)
	v_mfma_f32_32x32x16_bf16 v[34:49], v[146:149], v[158:161], v[34:49]
	s_waitcnt vmcnt(5)
; __device__ __forceinline__ int crow(int r, int hi) { return (r & 3) + 8 * (r >> 2) + 4 * hi; }
; #define MFMA32(a, b, c) __builtin_amdgcn_mfma_f32_32x32x16_bf16((a), (b), (c), 0, 0, 0)
; template <class Fin> __device__ __forceinline__ void ctx_gemm(const bf16_t* A, int lda, const bf16_t* Bt, int K, const Fin& fin, uchar* lds) {
;     ...
;             acc0 = MFMA32(af, b0, acc0); acc1 = MFMA32(af, b1, acc1); acc2 = MFMA32(af, b2, acc2); acc3 = MFMA32(af, b3, acc3);
;         }
;         float* rw = red + wave * 4096 + l32;
; #pragma unroll
;         for (int r = 0; r < 16; ++r) { float* q = rw + crow(r, hi) * 128; q[0] = acc0[r]; q[32] = acc1[r]; q[64] = acc2[r]; q[96] = acc3[r]; }
;         __syncthreads();
;         const int row = tid >> 4, c8 = (tid & 15) * 8;
;         f32x4 s0 = {}, s1 = {};
; #pragma unroll
;         for (int w = 0; w < 8; ++w) { s0 += *(const f32x4*)(red + w * 4096 + row * 128 + c8); s1 += *(const f32x4*)(red + w * 4096 + row * 128 + c8 + 4); }
;         fin(tr * 32 + row, tc * 128 + c8, s0, s1);
	v_mfma_f32_32x32x16_bf16 v[50:65], v[146:149], v[162:165], v[50:65]
	s_waitcnt vmcnt(3)
	v_mfma_f32_32x32x16_bf16 v[2:17], v[166:169], v[170:173], v[2:17]
	s_waitcnt vmcnt(2)
	v_mfma_f32_32x32x16_bf16 v[18:33], v[166:169], v[174:177], v[18:33]
	s_waitcnt vmcnt(1)
	v_mfma_f32_32x32x16_bf16 v[34:49], v[166:169], v[178:181], v[34:49]
	s_waitcnt vmcnt(0)
	v_mfma_f32_32x32x16_bf16 v[50:65], v[166:169], v[182:185], v[50:65]
	s_nop 7
	ds_write2_b32 v81, v2, v18 offset1:32
	s_nop 2
	ds_write2_b32 v81, v34, v50 offset0:64 offset1:96
	ds_write2_b32 v81, v3, v19 offset0:128 offset1:160
	ds_write2_b32 v81, v35, v51 offset0:192 offset1:224
	ds_write2_b32 v0, v4, v20 offset1:32
	ds_write2_b32 v0, v36, v52 offset0:64 offset1:96
	ds_write2_b32 v0, v5, v21 offset0:128 offset1:160
	ds_write2_b32 v0, v37, v53 offset0:192 offset1:224
	v_add_u32_e32 v0, 0x1000, v81
	ds_write2_b32 v0, v6, v22 offset1:32
	ds_write2_b32 v0, v38, v54 offset0:64 offset1:96
	ds_write2_b32 v0, v7, v23 offset0:128 offset1:160
	ds_write2_b32 v0, v39, v55 offset0:192 offset1:224
	v_add_u32_e32 v0, 0x1400, v81
	ds_write2_b32 v0, v8, v24 offset1:32
	ds_write2_b32 v0, v40, v56 offset0:64 offset1:96
	ds_write2_b32 v0, v9, v25 offset0:128 offset1:160
	ds_write2_b32 v0, v41, v57 offset0:192 offset1:224
	v_add_u32_e32 v0, 0x2000, v81
	ds_write2_b32 v0, v10, v26 offset1:32
	ds_write2_b32 v0, v42, v58 offset0:64 offset1:96
	ds_write2_b32 v0, v11, v27 offset0:128 offset1:160
	ds_write2_b32 v0, v43, v59 offset0:192 offset1:224
	v_add_u32_e32 v0, 0x2400, v81
	ds_write2_b32 v0, v12, v28 offset1:32
	ds_write2_b32 v0, v44, v60 offset0:64 offset1:96
	ds_write2_b32 v0, v13, v29 offset0:128 offset1:160
	ds_write2_b32 v0, v45, v61 offset0:192 offset1:224
	v_add_u32_e32 v0, 0x3000, v81
	ds_write2_b32 v0, v14, v30 offset1:32
	ds_write2_b32 v0, v46, v62 offset0:64 offset1:96
	ds_write2_b32 v0, v15, v31 offset0:128 offset1:160
	ds_write2_b32 v0, v47, v63 offset0:192 offset1:224
	v_add_u32_e32 v0, 0x3400, v81
	ds_write2_b32 v0, v16, v32 offset1:32
	ds_write2_b32 v0, v48, v64 offset0:64 offset1:96
	ds_write2_b32 v0, v17, v33 offset0:128 offset1:160
	ds_write2_b32 v0, v49, v65 offset0:192 offset1:224
	s_waitcnt lgkmcnt(0)
	s_barrier
	ds_read_b128 v[2:5], v84
	ds_read_b128 v[6:9], v84 offset:16
	v_add_u32_e32 v18, s7, v82
	v_ashrrev_i32_e32 v19, 31, v18
	v_or_b32_e32 v0, s8, v83
	s_waitcnt lgkmcnt(1)
	v_pk_add_f32 v[10:11], v[4:5], 0 op_sel_hi:[1,0]
	v_pk_add_f32 v[12:13], v[2:3], 0 op_sel_hi:[1,0]
	ds_read_b128 v[2:5], v84 offset:16384
	s_waitcnt lgkmcnt(1)
	v_pk_add_f32 v[8:9], v[8:9], 0 op_sel_hi:[1,0]
	v_pk_add_f32 v[6:7], v[6:7], 0 op_sel_hi:[1,0]
	v_lshlrev_b64 v[18:19], 12, v[18:19]
	v_lshlrev_b32_e32 v0, 2, v0
	s_waitcnt lgkmcnt(0)
	v_pk_add_f32 v[10:11], v[10:11], v[4:5]
	v_pk_add_f32 v[12:13], v[12:13], v[2:3]
	ds_read_b128 v[2:5], v84 offset:16400
	v_lshl_add_u64 v[18:19], s[86:87], 0, v[18:19]
	v_lshl_add_u64 v[26:27], v[18:19], 0, v[0:1]
	s_waitcnt lgkmcnt(0)
	v_pk_add_f32 v[8:9], v[8:9], v[4:5]
	v_pk_add_f32 v[6:7], v[6:7], v[2:3]
	ds_read_b128 v[2:5], v84 offset:32768
	s_waitcnt lgkmcnt(0)
	v_pk_add_f32 v[10:11], v[10:11], v[4:5]
	v_pk_add_f32 v[12:13], v[12:13], v[2:3]
	ds_read_b128 v[2:5], v84 offset:32784
	s_waitcnt lgkmcnt(0)
	v_pk_add_f32 v[8:9], v[8:9], v[4:5]
	v_pk_add_f32 v[6:7], v[6:7], v[2:3]
	ds_read_b128 v[2:5], v84 offset:49152
	s_waitcnt lgkmcnt(0)
	v_pk_add_f32 v[10:11], v[10:11], v[4:5]
	v_pk_add_f32 v[12:13], v[12:13], v[2:3]
	ds_read_b128 v[2:5], v84 offset:49168
	s_waitcnt lgkmcnt(0)
	v_pk_add_f32 v[8:9], v[8:9], v[4:5]
	v_pk_add_f32 v[6:7], v[6:7], v[2:3]
	ds_read_b128 v[2:5], v85
	s_waitcnt lgkmcnt(0)
	v_pk_add_f32 v[10:11], v[10:11], v[4:5]
	v_pk_add_f32 v[12:13], v[12:13], v[2:3]
	ds_read_b128 v[2:5], v86
	s_waitcnt lgkmcnt(0)
	v_pk_add_f32 v[8:9], v[8:9], v[4:5]
	v_pk_add_f32 v[6:7], v[6:7], v[2:3]
	ds_read_b128 v[2:5], v87
	s_waitcnt lgkmcnt(0)
	v_pk_add_f32 v[10:11], v[10:11], v[4:5]
	v_pk_add_f32 v[12:13], v[12:13], v[2:3]
	ds_read_b128 v[2:5], v88
	s_waitcnt lgkmcnt(0)
	v_pk_add_f32 v[8:9], v[8:9], v[4:5]
	v_pk_add_f32 v[6:7], v[6:7], v[2:3]
	ds_read_b128 v[2:5], v89
	s_waitcnt lgkmcnt(0)
	v_pk_add_f32 v[10:11], v[10:11], v[4:5]
	v_pk_add_f32 v[12:13], v[12:13], v[2:3]
	ds_read_b128 v[2:5], v90
	s_waitcnt lgkmcnt(0)
	v_pk_add_f32 v[14:15], v[8:9], v[4:5]
	v_pk_add_f32 v[16:17], v[6:7], v[2:3]
	ds_read_b128 v[4:7], v91
	s_waitcnt lgkmcnt(0)
	v_pk_add_f32 v[2:3], v[10:11], v[6:7]
	ds_read_b128 v[8:11], v92
	v_pk_add_f32 v[4:5], v[12:13], v[4:5]
	s_waitcnt lgkmcnt(0)
	v_pk_add_f32 v[6:7], v[14:15], v[10:11]
	v_pk_add_f32 v[8:9], v[16:17], v[8:9]
	global_load_dwordx4 v[10:13], v0, s[36:37] offset:16
	global_load_dwordx4 v[14:17], v0, s[36:37]
	global_load_dwordx4 v[18:21], v[26:27], off offset:16
	global_load_dwordx4 v[22:25], v[26:27], off
	s_waitcnt vmcnt(0)
	v_pk_fma_f32 v[16:17], v[2:3], v[16:17], v[24:25]
	v_pk_fma_f32 v[14:15], v[4:5], v[14:15], v[22:23]
	v_pk_fma_f32 v[4:5], v[6:7], v[12:13], v[20:21]
	v_pk_fma_f32 v[2:3], v[8:9], v[10:11], v[18:19]
	global_store_dwordx4 v[26:27], v[14:17], off
	global_store_dwordx4 v[26:27], v[2:5], off offset:16
	s_barrier
	s_cbranch_scc1 .LBB0_1539

; #define MFMA32(a, b, c) __builtin_amdgcn_mfma_f32_32x32x16_bf16((a), (b), (c), 0, 0, 0)
; template <class Fin> __device__ __forceinline__ void ctx_gemm(const bf16_t* A, int lda, const bf16_t* Bt, int K, const Fin& fin, uchar* lds) {
;     ...
;     for (int id = blockIdx.x; id < 256; id += gridDim.x) {
;         const int tr = id >> 3, tc = id & 7;
;         const bf16_t* ap = A + (size_t)(tr * 32 + l32) * lda + wave * kw + 8 * hi;
;         const bf16_t* bp = Bt + (size_t)(tc * 128 + l32) * K + wave * kw + 8 * hi;
;         f32x16 acc0 = {}, acc1 = {}, acc2 = {}, acc3 = {};
; #pragma unroll 8
;         for (int s = 0; s < nst; ++s) {
;             const bf16x8 af = *(const bf16x8*)(ap + 16 * s);
;             const bf16x8 b0 = *(const bf16x8*)(bp + 16 * s), b1 = *(const bf16x8*)(bp + (size_t)32 * K + 16 * s), b2 = *(const bf16x8*)(bp + (size_t)64 * K + 16 * s), b3 = *(const bf16x8*)(bp + (size_t)96 * K + 16 * s);
;             acc0 = MFMA32(af, b0, acc0); acc1 = MFMA32(af, b1, acc1); acc2 = MFMA32(af, b2, acc2); acc3 = MFMA32(af, b3, acc3);
.LBB0_1887:
	s_and_b32 s7, s4, 0xffffffe0
	v_or_b32_e32 v0, s7, v80
	v_mad_i64_i32 v[78:79], s[8:9], v0, s16, v[66:67]
	s_and_b32 s8, s5, 0x380
	s_nop 0
	v_or_b32_e32 v0, s8, v80
	v_mul_u32_u24_e32 v0, 0xb00, v0
	v_lshlrev_b32_e32 v0, 1, v0
	v_lshl_add_u64 v[74:75], v[68:69], 0, v[0:1]
	v_add_co_u32_e32 v76, vcc, 0x2c000, v74
	global_load_dwordx4 v[50:53], v[78:79], off
	global_load_dwordx4 v[2:5], v[74:75], off
	v_addc_co_u32_e32 v77, vcc, 0, v75, vcc
	v_add_co_u32_e32 v72, vcc, 0x58000, v74
	s_waitcnt lgkmcnt(0)
	global_load_dwordx4 v[18:21], v[76:77], off
	v_addc_co_u32_e32 v73, vcc, 0, v75, vcc
	v_add_co_u32_e32 v70, vcc, 0x84000, v74
	global_load_dwordx4 v[34:37], v[72:73], off
	s_nop 0
	v_addc_co_u32_e32 v71, vcc, 0, v75, vcc
	global_load_dwordx4 v[54:57], v[70:71], off
	global_load_dwordx4 v[94:97], v[78:79], off offset:32
	global_load_dwordx4 v[98:101], v[74:75], off offset:32
	global_load_dwordx4 v[102:105], v[76:77], off offset:32
	global_load_dwordx4 v[106:109], v[72:73], off offset:32
	global_load_dwordx4 v[110:113], v[70:71], off offset:32
	v_add_u32_e32 v0, 0x400, v81
	s_add_i32 s6, s6, s90
	s_add_i32 s5, s5, s17
	s_add_i32 s4, s4, s64
	s_cmpk_lt_i32 s6, 0x100
	global_load_dwordx4 v[146:149], v[78:79], off offset:64
	global_load_dwordx4 v[150:153], v[74:75], off offset:64
	global_load_dwordx4 v[154:157], v[76:77], off offset:64
	global_load_dwordx4 v[158:161], v[72:73], off offset:64
	global_load_dwordx4 v[162:165], v[70:71], off offset:64
	global_load_dwordx4 v[166:169], v[78:79], off offset:96
	global_load_dwordx4 v[170:173], v[74:75], off offset:96
	global_load_dwordx4 v[174:177], v[76:77], off offset:96
	global_load_dwordx4 v[178:181], v[72:73], off offset:96
	global_load_dwordx4 v[182:185], v[70:71], off offset:96
	global_load_dwordx4 v[194:197], v[78:79], off offset:128
	global_load_dwordx4 v[198:201], v[74:75], off offset:128
	global_load_dwordx4 v[202:205], v[76:77], off offset:128
	global_load_dwordx4 v[220:223], v[72:73], off offset:128
	global_load_dwordx4 v[224:227], v[70:71], off offset:128
	s_waitcnt vmcnt(15)
	v_mfma_f32_32x32x16_bf16 v[2:17], v[50:53], v[2:5], 0
	v_mfma_f32_32x32x16_bf16 v[18:33], v[50:53], v[18:21], 0
	v_mfma_f32_32x32x16_bf16 v[34:49], v[50:53], v[34:37], 0
	v_mfma_f32_32x32x16_bf16 v[50:65], v[50:53], v[54:57], 0
	v_mfma_f32_32x32x16_bf16 v[2:17], v[94:97], v[98:101], v[2:17]
	v_mfma_f32_32x32x16_bf16 v[18:33], v[94:97], v[102:105], v[18:33]
	v_mfma_f32_32x32x16_bf16 v[34:49], v[94:97], v[106:109], v[34:49]
	v_mfma_f32_32x32x16_bf16 v[50:65], v[94:97], v[110:113], v[50:65]
	global_load_dwordx4 v[94:97], v[78:79], off offset:160
	global_load_dwordx4 v[98:101], v[74:75], off offset:160
	global_load_dwordx4 v[102:105], v[76:77], off offset:160
	global_load_dwordx4 v[106:109], v[72:73], off offset:160
	global_load_dwordx4 v[110:113], v[70:71], off offset:160
	s_waitcnt vmcnt(18)
	v_mfma_f32_32x32x16_bf16 v[2:17], v[146:149], v[150:153], v[2:17]
	s_waitcnt vmcnt(17)
	v_mfma_f32_32x32x16_bf16 v[18:33], v[146:149], v[154:157], v[18:33]
	s_waitcnt vmcnt(16)
	v_mfma_f32_32x32x16_bf16 v[34:49], v[146:149], v[158:161], v[34:49]
	s_waitcnt vmcnt(15)
	v_mfma_f32_32x32x16_bf16 v[50:65], v[146:149], v[162:165], v[50:65]
	global_load_dwordx4 v[146:149], v[78:79], off offset:192
	global_load_dwordx4 v[150:153], v[74:75], off offset:192
	global_load_dwordx4 v[154:157], v[76:77], off offset:192
	global_load_dwordx4 v[158:161], v[72:73], off offset:192
	global_load_dwordx4 v[162:165], v[70:71], off offset:192
	s_waitcnt vmcnt(18)
	v_mfma_f32_32x32x16_bf16 v[2:17], v[166:169], v[170:173], v[2:17]
	s_waitcnt vmcnt(17)
	v_mfma_f32_32x32x16_bf16 v[18:33], v[166:169], v[174:177], v[18:33]
	s_waitcnt vmcnt(16)
	v_mfma_f32_32x32x16_bf16 v[34:49], v[166:169], v[178:181], v[34:49]
	s_waitcnt vmcnt(15)
	v_mfma_f32_32x32x16_bf16 v[50:65], v[166:169], v[182:185], v[50:65]
	global_load_dwordx4 v[166:169], v[78:79], off offset:224
	global_load_dwordx4 v[170:173], v[74:75], off offset:224
	global_load_dwordx4 v[174:177], v[76:77], off offset:224
	global_load_dwordx4 v[178:181], v[72:73], off offset:224
	global_load_dwordx4 v[182:185], v[70:71], off offset:224
	s_waitcnt vmcnt(18)
	v_mfma_f32_32x32x16_bf16 v[2:17], v[194:197], v[198:201], v[2:17]
	s_waitcnt vmcnt(17)
	v_mfma_f32_32x32x16_bf16 v[18:33], v[194:197], v[202:205], v[18:33]
	s_waitcnt vmcnt(16)
	v_mfma_f32_32x32x16_bf16 v[34:49], v[194:197], v[220:223], v[34:49]
	s_waitcnt vmcnt(15)
	v_mfma_f32_32x32x16_bf16 v[50:65], v[194:197], v[224:227], v[50:65]
	global_load_dwordx4 v[194:197], v[78:79], off offset:256
	global_load_dwordx4 v[198:201], v[74:75], off offset:256
	global_load_dwordx4 v[202:205], v[76:77], off offset:256
	global_load_dwordx4 v[220:223], v[72:73], off offset:256
	global_load_dwordx4 v[224:227], v[70:71], off offset:256
	s_waitcnt vmcnt(18)
	v_mfma_f32_32x32x16_bf16 v[2:17], v[94:97], v[98:101], v[2:17]
	s_waitcnt vmcnt(17)
	v_mfma_f32_32x32x16_bf16 v[18:33], v[94:97], v[102:105], v[18:33]
	s_waitcnt vmcnt(16)
	v_mfma_f32_32x32x16_bf16 v[34:49], v[94:97], v[106:109], v[34:49]
	s_waitcnt vmcnt(15)
	v_mfma_f32_32x32x16_bf16 v[50:65], v[94:97], v[110:113], v[50:65]
	global_load_dwordx4 v[94:97], v[78:79], off offset:288
	global_load_dwordx4 v[98:101], v[74:75], off offset:288
	global_load_dwordx4 v[102:105], v[76:77], off offset:288
	global_load_dwordx4 v[106:109], v[72:73], off offset:288
	global_load_dwordx4 v[110:113], v[70:71], off offset:288
	s_waitcnt vmcnt(18)
	v_mfma_f32_32x32x16_bf16 v[2:17], v[146:149], v[150:153], v[2:17]
	s_waitcnt vmcnt(17)
	v_mfma_f32_32x32x16_bf16 v[18:33], v[146:149], v[154:157], v[18:33]
	s_waitcnt vmcnt(16)
; #define MFMA32(a, b, c) __builtin_amdgcn_mfma_f32_32x32x16_bf16((a), (b), (c), 0, 0, 0)
; template <class Fin> __device__ __forceinline__ void ctx_gemm(const bf16_t* A, int lda, const bf16_t* Bt, int K, const Fin& fin, uchar* lds) {
;     ...
; #pragma unroll 8
;         for (int s = 0; s < nst; ++s) {
;             const bf16x8 af = *(const bf16x8*)(ap + 16 * s);
;             const bf16x8 b0 = *(const bf16x8*)(bp + 16 * s), b1 = *(const bf16x8*)(bp + (size_t)32 * K + 16 * s), b2 = *(const bf16x8*)(bp + (size_t)64 * K + 16 * s), b3 = *(const bf16x8*)(bp + (size_t)96 * K + 16 * s);
;             acc0 = MFMA32(af, b0, acc0); acc1 = MFMA32(af, b1, acc1); acc2 = MFMA32(af, b2, acc2); acc3 = MFMA32(af, b3, acc3);
	v_mfma_f32_32x32x16_bf16 v[34:49], v[146:149], v[158:161], v[34:49]
	s_waitcnt vmcnt(15)
	v_mfma_f32_32x32x16_bf16 v[50:65], v[146:149], v[162:165], v[50:65]
	global_load_dwordx4 v[146:149], v[78:79], off offset:320
	global_load_dwordx4 v[150:153], v[74:75], off offset:320
	global_load_dwordx4 v[154:157], v[76:77], off offset:320
	global_load_dwordx4 v[158:161], v[72:73], off offset:320
	global_load_dwordx4 v[162:165], v[70:71], off offset:320
	s_waitcnt vmcnt(18)
	v_mfma_f32_32x32x16_bf16 v[2:17], v[166:169], v[170:173], v[2:17]
	s_waitcnt vmcnt(17)
	v_mfma_f32_32x32x16_bf16 v[18:33], v[166:169], v[174:177], v[18:33]
	s_waitcnt vmcnt(16)
	v_mfma_f32_32x32x16_bf16 v[34:49], v[166:169], v[178:181], v[34:49]
	s_waitcnt vmcnt(15)
	v_mfma_f32_32x32x16_bf16 v[50:65], v[166:169], v[182:185], v[50:65]
	global_load_dwordx4 v[166:169], v[78:79], off offset:352
	global_load_dwordx4 v[170:173], v[74:75], off offset:352
	global_load_dwordx4 v[174:177], v[76:77], off offset:352
	global_load_dwordx4 v[178:181], v[72:73], off offset:352
	global_load_dwordx4 v[182:185], v[70:71], off offset:352
	s_waitcnt vmcnt(18)
	v_mfma_f32_32x32x16_bf16 v[2:17], v[194:197], v[198:201], v[2:17]
	s_waitcnt vmcnt(17)
	v_mfma_f32_32x32x16_bf16 v[18:33], v[194:197], v[202:205], v[18:33]
	s_waitcnt vmcnt(16)
	v_mfma_f32_32x32x16_bf16 v[34:49], v[194:197], v[220:223], v[34:49]
	s_waitcnt vmcnt(15)
	v_mfma_f32_32x32x16_bf16 v[50:65], v[194:197], v[224:227], v[50:65]
	global_load_dwordx4 v[194:197], v[78:79], off offset:384
	global_load_dwordx4 v[198:201], v[74:75], off offset:384
	global_load_dwordx4 v[202:205], v[76:77], off offset:384
	global_load_dwordx4 v[220:223], v[72:73], off offset:384
	global_load_dwordx4 v[224:227], v[70:71], off offset:384
	s_waitcnt vmcnt(18)
	v_mfma_f32_32x32x16_bf16 v[2:17], v[94:97], v[98:101], v[2:17]
	s_waitcnt vmcnt(17)
	v_mfma_f32_32x32x16_bf16 v[18:33], v[94:97], v[102:105], v[18:33]
	s_waitcnt vmcnt(16)
	v_mfma_f32_32x32x16_bf16 v[34:49], v[94:97], v[106:109], v[34:49]
	s_waitcnt vmcnt(15)
	v_mfma_f32_32x32x16_bf16 v[50:65], v[94:97], v[110:113], v[50:65]
	global_load_dwordx4 v[94:97], v[78:79], off offset:416
	global_load_dwordx4 v[98:101], v[74:75], off offset:416
	global_load_dwordx4 v[102:105], v[76:77], off offset:416
	global_load_dwordx4 v[106:109], v[72:73], off offset:416
	global_load_dwordx4 v[110:113], v[70:71], off offset:416
	s_waitcnt vmcnt(18)
	v_mfma_f32_32x32x16_bf16 v[2:17], v[146:149], v[150:153], v[2:17]
	s_waitcnt vmcnt(17)
	v_mfma_f32_32x32x16_bf16 v[18:33], v[146:149], v[154:157], v[18:33]
	s_waitcnt vmcnt(16)
	v_mfma_f32_32x32x16_bf16 v[34:49], v[146:149], v[158:161], v[34:49]
	s_waitcnt vmcnt(15)
	v_mfma_f32_32x32x16_bf16 v[50:65], v[146:149], v[162:165], v[50:65]
	global_load_dwordx4 v[146:149], v[78:79], off offset:448
	global_load_dwordx4 v[150:153], v[74:75], off offset:448
	global_load_dwordx4 v[154:157], v[76:77], off offset:448
	global_load_dwordx4 v[158:161], v[72:73], off offset:448
	global_load_dwordx4 v[162:165], v[70:71], off offset:448
	s_waitcnt vmcnt(18)
	v_mfma_f32_32x32x16_bf16 v[2:17], v[166:169], v[170:173], v[2:17]
	s_waitcnt vmcnt(17)
	v_mfma_f32_32x32x16_bf16 v[18:33], v[166:169], v[174:177], v[18:33]
	s_waitcnt vmcnt(16)
	v_mfma_f32_32x32x16_bf16 v[34:49], v[166:169], v[178:181], v[34:49]
	s_waitcnt vmcnt(15)
	v_mfma_f32_32x32x16_bf16 v[50:65], v[166:169], v[182:185], v[50:65]
	global_load_dwordx4 v[166:169], v[78:79], off offset:480
	global_load_dwordx4 v[170:173], v[74:75], off offset:480
	global_load_dwordx4 v[174:177], v[76:77], off offset:480
	global_load_dwordx4 v[178:181], v[72:73], off offset:480
	global_load_dwordx4 v[182:185], v[70:71], off offset:480
	s_waitcnt vmcnt(18)
	v_mfma_f32_32x32x16_bf16 v[2:17], v[194:197], v[198:201], v[2:17]
	s_waitcnt vmcnt(17)
	v_mfma_f32_32x32x16_bf16 v[18:33], v[194:197], v[202:205], v[18:33]
	s_waitcnt vmcnt(16)
	v_mfma_f32_32x32x16_bf16 v[34:49], v[194:197], v[220:223], v[34:49]
	s_waitcnt vmcnt(15)
	v_mfma_f32_32x32x16_bf16 v[50:65], v[194:197], v[224:227], v[50:65]
	global_load_dwordx4 v[194:197], v[78:79], off offset:512
	global_load_dwordx4 v[198:201], v[74:75], off offset:512
	global_load_dwordx4 v[202:205], v[76:77], off offset:512
	global_load_dwordx4 v[220:223], v[72:73], off offset:512
	global_load_dwordx4 v[224:227], v[70:71], off offset:512
	s_waitcnt vmcnt(18)
	v_mfma_f32_32x32x16_bf16 v[2:17], v[94:97], v[98:101], v[2:17]
	s_waitcnt vmcnt(17)
	v_mfma_f32_32x32x16_bf16 v[18:33], v[94:97], v[102:105], v[18:33]
	s_waitcnt vmcnt(16)
	v_mfma_f32_32x32x16_bf16 v[34:49], v[94:97], v[106:109], v[34:49]
	s_waitcnt vmcnt(15)
	v_mfma_f32_32x32x16_bf16 v[50:65], v[94:97], v[110:113], v[50:65]
	global_load_dwordx4 v[94:97], v[78:79], off offset:544
	global_load_dwordx4 v[98:101], v[74:75], off offset:544
	global_load_dwordx4 v[102:105], v[76:77], off offset:544
	global_load_dwordx4 v[106:109], v[72:73], off offset:544
	global_load_dwordx4 v[110:113], v[70:71], off offset:544
	s_waitcnt vmcnt(18)
	v_mfma_f32_32x32x16_bf16 v[2:17], v[146:149], v[150:153], v[2:17]
	s_waitcnt vmcnt(17)
	v_mfma_f32_32x32x16_bf16 v[18:33], v[146:149], v[154:157], v[18:33]
	s_waitcnt vmcnt(16)
	v_mfma_f32_32x32x16_bf16 v[34:49], v[146:149], v[158:161], v[34:49]
	s_waitcnt vmcnt(15)
	v_mfma_f32_32x32x16_bf16 v[50:65], v[146:149], v[162:165], v[50:65]
	global_load_dwordx4 v[146:149], v[78:79], off offset:576
	global_load_dwordx4 v[150:153], v[74:75], off offset:576
	global_load_dwordx4 v[154:157], v[76:77], off offset:576
	global_load_dwordx4 v[158:161], v[72:73], off offset:576
	global_load_dwordx4 v[162:165], v[70:71], off offset:576
	s_waitcnt vmcnt(18)
; __device__ __forceinline__ int crow(int r, int hi) { return (r & 3) + 8 * (r >> 2) + 4 * hi; }
; #define MFMA32(a, b, c) __builtin_amdgcn_mfma_f32_32x32x16_bf16((a), (b), (c), 0, 0, 0)
; template <class Fin> __device__ __forceinline__ void ctx_gemm(const bf16_t* A, int lda, const bf16_t* Bt, int K, const Fin& fin, uchar* lds) {
;     ...
; #pragma unroll 8
;         for (int s = 0; s < nst; ++s) {
;             const bf16x8 af = *(const bf16x8*)(ap + 16 * s);
;             const bf16x8 b0 = *(const bf16x8*)(bp + 16 * s), b1 = *(const bf16x8*)(bp + (size_t)32 * K + 16 * s), b2 = *(const bf16x8*)(bp + (size_t)64 * K + 16 * s), b3 = *(const bf16x8*)(bp + (size_t)96 * K + 16 * s);
;             acc0 = MFMA32(af, b0, acc0); acc1 = MFMA32(af, b1, acc1); acc2 = MFMA32(af, b2, acc2); acc3 = MFMA32(af, b3, acc3);
;         }
;         float* rw = red + wave * 4096 + l32;
; #pragma unroll
;         for (int r = 0; r < 16; ++r) { float* q = rw + crow(r, hi) * 128; q[0] = acc0[r]; q[32] = acc1[r]; q[64] = acc2[r]; q[96] = acc3[r]; }
;         __syncthreads();
	v_mfma_f32_32x32x16_bf16 v[2:17], v[166:169], v[170:173], v[2:17]
	s_waitcnt vmcnt(17)
	v_mfma_f32_32x32x16_bf16 v[18:33], v[166:169], v[174:177], v[18:33]
	s_waitcnt vmcnt(16)
	v_mfma_f32_32x32x16_bf16 v[34:49], v[166:169], v[178:181], v[34:49]
	s_waitcnt vmcnt(15)
	v_mfma_f32_32x32x16_bf16 v[50:65], v[166:169], v[182:185], v[50:65]
	global_load_dwordx4 v[166:169], v[78:79], off offset:608
	global_load_dwordx4 v[170:173], v[74:75], off offset:608
	global_load_dwordx4 v[174:177], v[76:77], off offset:608
	global_load_dwordx4 v[178:181], v[72:73], off offset:608
	global_load_dwordx4 v[182:185], v[70:71], off offset:608
	s_waitcnt vmcnt(18)
	v_mfma_f32_32x32x16_bf16 v[2:17], v[194:197], v[198:201], v[2:17]
	s_waitcnt vmcnt(17)
	v_mfma_f32_32x32x16_bf16 v[18:33], v[194:197], v[202:205], v[18:33]
	s_waitcnt vmcnt(16)
	v_mfma_f32_32x32x16_bf16 v[34:49], v[194:197], v[220:223], v[34:49]
	s_waitcnt vmcnt(15)
	v_mfma_f32_32x32x16_bf16 v[50:65], v[194:197], v[224:227], v[50:65]
	global_load_dwordx4 v[194:197], v[78:79], off offset:640
	global_load_dwordx4 v[198:201], v[74:75], off offset:640
	global_load_dwordx4 v[202:205], v[76:77], off offset:640
	global_load_dwordx4 v[220:223], v[72:73], off offset:640
	global_load_dwordx4 v[224:227], v[70:71], off offset:640
	s_waitcnt vmcnt(18)
	v_mfma_f32_32x32x16_bf16 v[2:17], v[94:97], v[98:101], v[2:17]
	s_waitcnt vmcnt(17)
	v_mfma_f32_32x32x16_bf16 v[18:33], v[94:97], v[102:105], v[18:33]
	s_waitcnt vmcnt(16)
	v_mfma_f32_32x32x16_bf16 v[34:49], v[94:97], v[106:109], v[34:49]
	s_waitcnt vmcnt(15)
	v_mfma_f32_32x32x16_bf16 v[50:65], v[94:97], v[110:113], v[50:65]
	global_load_dwordx4 v[94:97], v[78:79], off offset:672
	global_load_dwordx4 v[98:101], v[74:75], off offset:672
	global_load_dwordx4 v[102:105], v[76:77], off offset:672
	global_load_dwordx4 v[106:109], v[72:73], off offset:672
	global_load_dwordx4 v[110:113], v[70:71], off offset:672
	s_waitcnt vmcnt(18)
	v_mfma_f32_32x32x16_bf16 v[2:17], v[146:149], v[150:153], v[2:17]
	s_waitcnt vmcnt(17)
	v_mfma_f32_32x32x16_bf16 v[18:33], v[146:149], v[154:157], v[18:33]
	s_waitcnt vmcnt(16)
	v_mfma_f32_32x32x16_bf16 v[34:49], v[146:149], v[158:161], v[34:49]
	s_waitcnt vmcnt(15)
	v_mfma_f32_32x32x16_bf16 v[50:65], v[146:149], v[162:165], v[50:65]
	s_waitcnt vmcnt(13)
	v_mfma_f32_32x32x16_bf16 v[2:17], v[166:169], v[170:173], v[2:17]
	s_waitcnt vmcnt(12)
	v_mfma_f32_32x32x16_bf16 v[18:33], v[166:169], v[174:177], v[18:33]
	s_waitcnt vmcnt(11)
	v_mfma_f32_32x32x16_bf16 v[34:49], v[166:169], v[178:181], v[34:49]
	s_waitcnt vmcnt(10)
	v_mfma_f32_32x32x16_bf16 v[50:65], v[166:169], v[182:185], v[50:65]
	s_waitcnt vmcnt(8)
	v_mfma_f32_32x32x16_bf16 v[2:17], v[194:197], v[198:201], v[2:17]
	s_waitcnt vmcnt(7)
	v_mfma_f32_32x32x16_bf16 v[18:33], v[194:197], v[202:205], v[18:33]
	s_waitcnt vmcnt(6)
	v_mfma_f32_32x32x16_bf16 v[34:49], v[194:197], v[220:223], v[34:49]
	s_waitcnt vmcnt(5)
	v_mfma_f32_32x32x16_bf16 v[50:65], v[194:197], v[224:227], v[50:65]
	s_waitcnt vmcnt(3)
	v_mfma_f32_32x32x16_bf16 v[2:17], v[94:97], v[98:101], v[2:17]
	s_waitcnt vmcnt(2)
	v_mfma_f32_32x32x16_bf16 v[18:33], v[94:97], v[102:105], v[18:33]
	s_waitcnt vmcnt(1)
	v_mfma_f32_32x32x16_bf16 v[34:49], v[94:97], v[106:109], v[34:49]
	s_waitcnt vmcnt(0)
	v_mfma_f32_32x32x16_bf16 v[50:65], v[94:97], v[110:113], v[50:65]
	s_nop 7
	ds_write2_b32 v81, v2, v18 offset1:32
	s_nop 2
	ds_write2_b32 v81, v34, v50 offset0:64 offset1:96
	ds_write2_b32 v81, v3, v19 offset0:128 offset1:160
	ds_write2_b32 v81, v35, v51 offset0:192 offset1:224
	ds_write2_b32 v0, v4, v20 offset1:32
	ds_write2_b32 v0, v36, v52 offset0:64 offset1:96
	ds_write2_b32 v0, v5, v21 offset0:128 offset1:160
	ds_write2_b32 v0, v37, v53 offset0:192 offset1:224
	v_add_u32_e32 v0, 0x1000, v81
	ds_write2_b32 v0, v6, v22 offset1:32
	ds_write2_b32 v0, v38, v54 offset0:64 offset1:96
	ds_write2_b32 v0, v7, v23 offset0:128 offset1:160
	ds_write2_b32 v0, v39, v55 offset0:192 offset1:224
	v_add_u32_e32 v0, 0x1400, v81
	ds_write2_b32 v0, v8, v24 offset1:32
	ds_write2_b32 v0, v40, v56 offset0:64 offset1:96
	ds_write2_b32 v0, v9, v25 offset0:128 offset1:160
	ds_write2_b32 v0, v41, v57 offset0:192 offset1:224
	v_add_u32_e32 v0, 0x2000, v81
	ds_write2_b32 v0, v10, v26 offset1:32
	ds_write2_b32 v0, v42, v58 offset0:64 offset1:96
	ds_write2_b32 v0, v11, v27 offset0:128 offset1:160
	ds_write2_b32 v0, v43, v59 offset0:192 offset1:224
	v_add_u32_e32 v0, 0x2400, v81
	ds_write2_b32 v0, v12, v28 offset1:32
	ds_write2_b32 v0, v44, v60 offset0:64 offset1:96
	ds_write2_b32 v0, v13, v29 offset0:128 offset1:160
	ds_write2_b32 v0, v45, v61 offset0:192 offset1:224
	v_add_u32_e32 v0, 0x3000, v81
	ds_write2_b32 v0, v14, v30 offset1:32
	ds_write2_b32 v0, v46, v62 offset0:64 offset1:96
	ds_write2_b32 v0, v15, v31 offset0:128 offset1:160
	ds_write2_b32 v0, v47, v63 offset0:192 offset1:224
	v_add_u32_e32 v0, 0x3400, v81
	ds_write2_b32 v0, v16, v32 offset1:32
	ds_write2_b32 v0, v48, v64 offset0:64 offset1:96
	ds_write2_b32 v0, v17, v33 offset0:128 offset1:160
	ds_write2_b32 v0, v49, v65 offset0:192 offset1:224
	s_waitcnt lgkmcnt(0)
	s_barrier
; template <class Fin> __device__ __forceinline__ void ctx_gemm(const bf16_t* A, int lda, const bf16_t* Bt, int K, const Fin& fin, uchar* lds) {
;     ...
;         const int row = tid >> 4, c8 = (tid & 15) * 8;
;         f32x4 s0 = {}, s1 = {};
; #pragma unroll
;         for (int w = 0; w < 8; ++w) { s0 += *(const f32x4*)(red + w * 4096 + row * 128 + c8); s1 += *(const f32x4*)(red + w * 4096 + row * 128 + c8 + 4); }
;         fin(tr * 32 + row, tc * 128 + c8, s0, s1);
	ds_read_b128 v[2:5], v84
	ds_read_b128 v[6:9], v84 offset:16
	v_or_b32_e32 v0, s8, v83
	v_lshlrev_b32_e32 v0, 2, v0
	v_add_u32_e32 v18, s7, v82
	s_waitcnt lgkmcnt(1)
	v_pk_add_f32 v[10:11], v[4:5], 0 op_sel_hi:[1,0]
	v_pk_add_f32 v[12:13], v[2:3], 0 op_sel_hi:[1,0]
	ds_read_b128 v[2:5], v84 offset:16384
	s_waitcnt lgkmcnt(1)
	v_pk_add_f32 v[8:9], v[8:9], 0 op_sel_hi:[1,0]
	v_pk_add_f32 v[6:7], v[6:7], 0 op_sel_hi:[1,0]
	v_ashrrev_i32_e32 v19, 31, v18
	s_waitcnt lgkmcnt(0)
	v_pk_add_f32 v[10:11], v[10:11], v[4:5]
	v_pk_add_f32 v[12:13], v[12:13], v[2:3]
	ds_read_b128 v[2:5], v84 offset:16400
	s_waitcnt lgkmcnt(0)
	v_pk_add_f32 v[8:9], v[8:9], v[4:5]
	v_pk_add_f32 v[6:7], v[6:7], v[2:3]
	ds_read_b128 v[2:5], v84 offset:32768
	s_waitcnt lgkmcnt(0)
	v_pk_add_f32 v[10:11], v[10:11], v[4:5]
	v_pk_add_f32 v[12:13], v[12:13], v[2:3]
	ds_read_b128 v[2:5], v84 offset:32784
	s_waitcnt lgkmcnt(0)
	v_pk_add_f32 v[8:9], v[8:9], v[4:5]
	v_pk_add_f32 v[6:7], v[6:7], v[2:3]
	ds_read_b128 v[2:5], v84 offset:49152
	s_waitcnt lgkmcnt(0)
	v_pk_add_f32 v[10:11], v[10:11], v[4:5]
	v_pk_add_f32 v[12:13], v[12:13], v[2:3]
	ds_read_b128 v[2:5], v84 offset:49168
	s_waitcnt lgkmcnt(0)
	v_pk_add_f32 v[8:9], v[8:9], v[4:5]
	v_pk_add_f32 v[6:7], v[6:7], v[2:3]
	ds_read_b128 v[2:5], v85
	s_waitcnt lgkmcnt(0)
	v_pk_add_f32 v[10:11], v[10:11], v[4:5]
	v_pk_add_f32 v[12:13], v[12:13], v[2:3]
	ds_read_b128 v[2:5], v86
	s_waitcnt lgkmcnt(0)
	v_pk_add_f32 v[8:9], v[8:9], v[4:5]
	v_pk_add_f32 v[6:7], v[6:7], v[2:3]
	ds_read_b128 v[2:5], v87
	s_waitcnt lgkmcnt(0)
	v_pk_add_f32 v[10:11], v[10:11], v[4:5]
	v_pk_add_f32 v[12:13], v[12:13], v[2:3]
	ds_read_b128 v[2:5], v88
	s_waitcnt lgkmcnt(0)
	v_pk_add_f32 v[8:9], v[8:9], v[4:5]
	v_pk_add_f32 v[6:7], v[6:7], v[2:3]
	ds_read_b128 v[2:5], v89
	s_waitcnt lgkmcnt(0)
	v_pk_add_f32 v[10:11], v[10:11], v[4:5]
	v_pk_add_f32 v[12:13], v[12:13], v[2:3]
	ds_read_b128 v[2:5], v90
	s_waitcnt lgkmcnt(0)
	v_pk_add_f32 v[14:15], v[8:9], v[4:5]
	v_pk_add_f32 v[16:17], v[6:7], v[2:3]
	ds_read_b128 v[4:7], v91
	s_waitcnt lgkmcnt(0)
	v_pk_add_f32 v[2:3], v[10:11], v[6:7]
	ds_read_b128 v[8:11], v92
	v_pk_add_f32 v[4:5], v[12:13], v[4:5]
	s_waitcnt lgkmcnt(0)
	v_pk_add_f32 v[6:7], v[14:15], v[10:11]
	v_pk_add_f32 v[8:9], v[16:17], v[8:9]
	global_load_dwordx4 v[10:13], v0, s[36:37] offset:16
	global_load_dwordx4 v[14:17], v0, s[36:37]
	s_waitcnt vmcnt(1)
	v_pk_mul_f32 v[26:27], v[10:11], 0.5 op_sel_hi:[1,0]
	v_lshlrev_b64 v[10:11], 12, v[18:19]
	v_lshl_add_u64 v[10:11], s[86:87], 0, v[10:11]
	v_lshl_add_u64 v[18:19], v[10:11], 0, v[0:1]
	s_waitcnt vmcnt(0)
	v_pk_mul_f32 v[20:21], v[16:17], 0.5 op_sel_hi:[1,0]
	v_pk_mul_f32 v[22:23], v[14:15], 0.5 op_sel_hi:[1,0]
	v_pk_mul_f32 v[24:25], v[12:13], 0.5 op_sel_hi:[1,0]
	global_load_dwordx4 v[10:13], v[18:19], off offset:16
	global_load_dwordx4 v[14:17], v[18:19], off
	s_waitcnt vmcnt(0)
	v_pk_fma_f32 v[16:17], v[2:3], v[20:21], v[16:17]
	v_pk_fma_f32 v[14:15], v[4:5], v[22:23], v[14:15]
	v_pk_fma_f32 v[4:5], v[6:7], v[24:25], v[12:13]
	v_pk_fma_f32 v[2:3], v[8:9], v[26:27], v[10:11]
	global_store_dwordx4 v[18:19], v[14:17], off
	global_store_dwordx4 v[18:19], v[2:5], off offset:16
	s_barrier
	s_cbranch_scc1 .LBB0_1887
